# GEMM K-loops: 44 LDS-DMA tile loads use scalar-base + 32-bit lane offset addressing, removing 8-12 64-bit VALU adds per iteration
# speedup vs baseline: 1.0110x; 1.0110x over previous
.LBB0_108:
	s_add_u32 s26, s50, 0xfff80080
	s_addc_u32 s27, s51, -1
	s_add_i32 s67, 0, 0x10000
	v_add_u32_e32 v134, s67, v180
	ds_read_b128 v[182:185], v134
	ds_read_b128 v[186:189], v134 offset:1024
	ds_read_b128 v[190:193], v134 offset:2048
	ds_read_b128 v[194:197], v134 offset:3072
	s_cmp_eq_u32 s66, 28
	s_cselect_b32 s53, s43, s27
	s_cselect_b32 s52, s62, s26
	s_cselect_b32 s27, s23, s65
	s_cselect_b32 s26, s63, s64
	s_add_i32 m0, s7, 0xc000
	ds_read_b128 v[198:201], v181
	ds_read_b128 v[202:205], v181 offset:1024
	ds_read_b128 v[206:209], v181 offset:2048
	ds_read_b128 v[210:213], v181 offset:3072
	ds_read_b128 v[214:217], v181 offset:4096
	ds_read_b128 v[218:221], v181 offset:5120
	ds_read_b128 v[222:225], v181 offset:6144
	ds_read_b128 v[226:229], v181 offset:7168
	global_load_lds_dwordx4 v162, s[50:51]
	s_add_i32 m0, s7, 0xe000
	s_nop 0
	global_load_lds_dwordx4 v164, s[50:51]
	s_waitcnt lgkmcnt(8)
	s_barrier
	s_waitcnt lgkmcnt(0)
	s_setprio 1
	s_waitcnt lgkmcnt(0)
	v_mfma_f32_16x16x32_bf16 v[126:129], v[182:185], v[198:201], v[126:129]
	v_mfma_f32_16x16x32_bf16 v[118:121], v[190:193], v[198:201], v[118:121]
	v_mfma_f32_16x16x32_bf16 v[110:113], v[182:185], v[206:209], v[110:113]
	v_mfma_f32_16x16x32_bf16 v[102:105], v[190:193], v[206:209], v[102:105]
	v_mfma_f32_16x16x32_bf16 v[94:97], v[182:185], v[214:217], v[94:97]
	v_mfma_f32_16x16x32_bf16 v[86:89], v[190:193], v[214:217], v[86:89]
	v_mfma_f32_16x16x32_bf16 v[78:81], v[182:185], v[222:225], v[78:81]
	v_mfma_f32_16x16x32_bf16 v[70:73], v[190:193], v[222:225], v[70:73]
	v_mfma_f32_16x16x32_bf16 v[126:129], v[186:189], v[202:205], v[126:129]
	v_mfma_f32_16x16x32_bf16 v[118:121], v[194:197], v[202:205], v[118:121]
	v_mfma_f32_16x16x32_bf16 v[110:113], v[186:189], v[210:213], v[110:113]
	v_mfma_f32_16x16x32_bf16 v[102:105], v[194:197], v[210:213], v[102:105]
	v_mfma_f32_16x16x32_bf16 v[94:97], v[186:189], v[218:221], v[94:97]
	v_mfma_f32_16x16x32_bf16 v[86:89], v[194:197], v[218:221], v[86:89]
	v_mfma_f32_16x16x32_bf16 v[78:81], v[186:189], v[226:229], v[78:81]
	v_mfma_f32_16x16x32_bf16 v[70:73], v[194:197], v[226:229], v[70:73]
	s_setprio 0
	s_barrier
	s_add_i32 s70, 0, 0x14000
	s_add_i32 s67, s67, s6
	v_add_u32_e32 v134, s70, v180
	v_lshl_add_u64 v[166:167], s[26:27], 0, v[0:1]
	s_mov_b32 m0, s67
	ds_read_b128 v[230:233], v134
	ds_read_b128 v[234:237], v134 offset:1024
	ds_read_b128 v[238:241], v134 offset:2048
	ds_read_b128 v[242:245], v134 offset:3072
	global_load_lds_dwordx4 v[166:167], off
	v_lshl_add_u64 v[246:247], s[26:27], 0, v[138:139]
	s_add_i32 m0, s67, 0x2000
	s_nop 0
	global_load_lds_dwordx4 v[246:247], off
	s_barrier
	s_waitcnt lgkmcnt(0)
	s_setprio 1
	s_waitcnt lgkmcnt(0)
	v_mfma_f32_16x16x32_bf16 v[122:125], v[230:233], v[198:201], v[122:125]
	v_mfma_f32_16x16x32_bf16 v[114:117], v[238:241], v[198:201], v[114:117]
	v_mfma_f32_16x16x32_bf16 v[106:109], v[230:233], v[206:209], v[106:109]
	v_mfma_f32_16x16x32_bf16 v[98:101], v[238:241], v[206:209], v[98:101]
	v_mfma_f32_16x16x32_bf16 v[90:93], v[230:233], v[214:217], v[90:93]
	v_mfma_f32_16x16x32_bf16 v[82:85], v[238:241], v[214:217], v[82:85]
	v_mfma_f32_16x16x32_bf16 v[74:77], v[230:233], v[222:225], v[74:77]
	v_mfma_f32_16x16x32_bf16 v[66:69], v[238:241], v[222:225], v[66:69]
	v_mfma_f32_16x16x32_bf16 v[122:125], v[234:237], v[202:205], v[122:125]
	v_mfma_f32_16x16x32_bf16 v[114:117], v[242:245], v[202:205], v[114:117]
	v_mfma_f32_16x16x32_bf16 v[106:109], v[234:237], v[210:213], v[106:109]
	v_mfma_f32_16x16x32_bf16 v[98:101], v[242:245], v[210:213], v[98:101]
	v_mfma_f32_16x16x32_bf16 v[90:93], v[234:237], v[218:221], v[90:93]
	v_mfma_f32_16x16x32_bf16 v[82:85], v[242:245], v[218:221], v[82:85]
	v_mfma_f32_16x16x32_bf16 v[74:77], v[234:237], v[226:229], v[74:77]
	v_mfma_f32_16x16x32_bf16 v[66:69], v[242:245], v[226:229], v[66:69]
	s_setprio 0
	s_mov_b32 m0, s7
	v_lshl_add_u64 v[248:249], s[52:53], 0, v[142:143]
	s_barrier
	ds_read_b128 v[198:201], v181 offset:16384
	ds_read_b128 v[202:205], v181 offset:17408
	ds_read_b128 v[206:209], v181 offset:18432
	ds_read_b128 v[210:213], v181 offset:19456
	ds_read_b128 v[214:217], v181 offset:20480
	ds_read_b128 v[218:221], v181 offset:21504
	ds_read_b128 v[222:225], v181 offset:22528
	ds_read_b128 v[226:229], v181 offset:23552
	global_load_lds_dwordx4 v[248:249], off
	v_lshl_add_u64 v[134:135], s[52:53], 0, v[140:141]
	s_mov_b32 m0, s14
	s_nop 0
	global_load_lds_dwordx4 v[134:135], off
	s_barrier
	s_waitcnt lgkmcnt(0)
	s_setprio 1
	s_waitcnt lgkmcnt(0)
	v_mfma_f32_16x16x32_bf16 v[62:65], v[182:185], v[198:201], v[62:65]
	v_mfma_f32_16x16x32_bf16 v[54:57], v[190:193], v[198:201], v[54:57]
	v_mfma_f32_16x16x32_bf16 v[46:49], v[182:185], v[206:209], v[46:49]
	v_mfma_f32_16x16x32_bf16 v[38:41], v[190:193], v[206:209], v[38:41]
	v_mfma_f32_16x16x32_bf16 v[30:33], v[182:185], v[214:217], v[30:33]
	v_mfma_f32_16x16x32_bf16 v[22:25], v[190:193], v[214:217], v[22:25]
	v_mfma_f32_16x16x32_bf16 v[14:17], v[182:185], v[222:225], v[14:17]
	v_mfma_f32_16x16x32_bf16 v[6:9], v[190:193], v[222:225], v[6:9]
	v_mfma_f32_16x16x32_bf16 v[62:65], v[186:189], v[202:205], v[62:65]
	v_mfma_f32_16x16x32_bf16 v[54:57], v[194:197], v[202:205], v[54:57]
	v_mfma_f32_16x16x32_bf16 v[46:49], v[186:189], v[210:213], v[46:49]
	v_mfma_f32_16x16x32_bf16 v[38:41], v[194:197], v[210:213], v[38:41]
	v_mfma_f32_16x16x32_bf16 v[30:33], v[186:189], v[218:221], v[30:33]
	v_mfma_f32_16x16x32_bf16 v[22:25], v[194:197], v[218:221], v[22:25]
	v_mfma_f32_16x16x32_bf16 v[14:17], v[186:189], v[226:229], v[14:17]
	v_mfma_f32_16x16x32_bf16 v[6:9], v[194:197], v[226:229], v[6:9]
	s_setprio 0
	s_barrier
	s_add_u32 s68, s26, 0x80000
	s_addc_u32 s69, s27, 0
	s_add_i32 s67, s70, s6
	s_mov_b32 m0, s67
	s_nop 0
	global_load_lds_dwordx4 v0, s[68:69]
	s_add_i32 m0, s67, 0x2000
	s_nop 0
	global_load_lds_dwordx4 v138, s[68:69]
	s_waitcnt vmcnt(6)
	s_barrier
	s_setprio 1
	v_mfma_f32_16x16x32_bf16 v[58:61], v[230:233], v[198:201], v[58:61]
	v_mfma_f32_16x16x32_bf16 v[50:53], v[238:241], v[198:201], v[50:53]
	v_mfma_f32_16x16x32_bf16 v[42:45], v[230:233], v[206:209], v[42:45]
	v_mfma_f32_16x16x32_bf16 v[34:37], v[238:241], v[206:209], v[34:37]
	v_mfma_f32_16x16x32_bf16 v[26:29], v[230:233], v[214:217], v[26:29]
	v_mfma_f32_16x16x32_bf16 v[18:21], v[238:241], v[214:217], v[18:21]
	v_mfma_f32_16x16x32_bf16 v[10:13], v[230:233], v[222:225], v[10:13]
	v_mfma_f32_16x16x32_bf16 v[2:5], v[238:241], v[222:225], v[2:5]
	v_mfma_f32_16x16x32_bf16 v[58:61], v[234:237], v[202:205], v[58:61]
	v_mfma_f32_16x16x32_bf16 v[50:53], v[242:245], v[202:205], v[50:53]
	v_mfma_f32_16x16x32_bf16 v[42:45], v[234:237], v[210:213], v[42:45]
	v_mfma_f32_16x16x32_bf16 v[34:37], v[242:245], v[210:213], v[34:37]
	v_mfma_f32_16x16x32_bf16 v[26:29], v[234:237], v[218:221], v[26:29]
	v_mfma_f32_16x16x32_bf16 v[18:21], v[242:245], v[218:221], v[18:21]
	v_mfma_f32_16x16x32_bf16 v[10:13], v[234:237], v[226:229], v[10:13]
	v_mfma_f32_16x16x32_bf16 v[2:5], v[242:245], v[226:229], v[2:5]
	s_setprio 0
	s_add_i32 s67, 0, 0x18000
	v_add_u32_e32 v194, s67, v180
	s_barrier
	ds_read_b128 v[182:185], v194
	ds_read_b128 v[186:189], v194 offset:1024
	ds_read_b128 v[190:193], v194 offset:2048
	ds_read_b128 v[194:197], v194 offset:3072
	s_add_u32 s52, s52, 0x80000
	s_addc_u32 s53, s53, 0
	s_mov_b32 m0, s54
	ds_read_b128 v[198:201], v181 offset:32768
	ds_read_b128 v[202:205], v181 offset:33792
	ds_read_b128 v[206:209], v181 offset:34816
	ds_read_b128 v[210:213], v181 offset:35840
	ds_read_b128 v[214:217], v181 offset:36864
	ds_read_b128 v[218:221], v181 offset:37888
	ds_read_b128 v[222:225], v181 offset:38912
	ds_read_b128 v[226:229], v181 offset:39936
	global_load_lds_dwordx4 v142, s[52:53]
	s_mov_b32 m0, s55
	s_nop 0
	global_load_lds_dwordx4 v140, s[52:53]
	s_waitcnt lgkmcnt(8)
	s_barrier
	s_waitcnt lgkmcnt(0)
	s_setprio 1
	s_waitcnt lgkmcnt(0)
	v_mfma_f32_16x16x32_bf16 v[126:129], v[182:185], v[198:201], v[126:129]
	v_mfma_f32_16x16x32_bf16 v[118:121], v[190:193], v[198:201], v[118:121]
	v_mfma_f32_16x16x32_bf16 v[110:113], v[182:185], v[206:209], v[110:113]
	v_mfma_f32_16x16x32_bf16 v[102:105], v[190:193], v[206:209], v[102:105]
	v_mfma_f32_16x16x32_bf16 v[94:97], v[182:185], v[214:217], v[94:97]
	v_mfma_f32_16x16x32_bf16 v[86:89], v[190:193], v[214:217], v[86:89]
	v_mfma_f32_16x16x32_bf16 v[78:81], v[182:185], v[222:225], v[78:81]
	v_mfma_f32_16x16x32_bf16 v[70:73], v[190:193], v[222:225], v[70:73]
	v_mfma_f32_16x16x32_bf16 v[126:129], v[186:189], v[202:205], v[126:129]
	v_mfma_f32_16x16x32_bf16 v[118:121], v[194:197], v[202:205], v[118:121]
	v_mfma_f32_16x16x32_bf16 v[110:113], v[186:189], v[210:213], v[110:113]
	v_mfma_f32_16x16x32_bf16 v[102:105], v[194:197], v[210:213], v[102:105]
	v_mfma_f32_16x16x32_bf16 v[94:97], v[186:189], v[218:221], v[94:97]
	v_mfma_f32_16x16x32_bf16 v[86:89], v[194:197], v[218:221], v[86:89]
	v_mfma_f32_16x16x32_bf16 v[78:81], v[186:189], v[226:229], v[78:81]
	v_mfma_f32_16x16x32_bf16 v[70:73], v[194:197], v[226:229], v[70:73]
	s_setprio 0
	s_barrier
	s_add_i32 s52, 0, 0x1c000
	s_add_i32 s53, s67, s6
	v_add_u32_e32 v242, s52, v180
	v_lshl_add_u64 v[166:167], v[166:167], 0, s[10:11]
	s_mov_b32 m0, s53
	ds_read_b128 v[230:233], v242
	ds_read_b128 v[234:237], v242 offset:1024
	ds_read_b128 v[238:241], v242 offset:2048
	ds_read_b128 v[242:245], v242 offset:3072
	global_load_lds_dwordx4 v[166:167], off
	v_lshl_add_u64 v[166:167], v[246:247], 0, s[10:11]
	s_add_i32 m0, s53, 0x2000
	s_nop 0
	global_load_lds_dwordx4 v[166:167], off
	s_barrier
	s_waitcnt lgkmcnt(0)
	s_setprio 1
	s_waitcnt lgkmcnt(0)
	v_mfma_f32_16x16x32_bf16 v[122:125], v[230:233], v[198:201], v[122:125]
	v_mfma_f32_16x16x32_bf16 v[114:117], v[238:241], v[198:201], v[114:117]
	v_mfma_f32_16x16x32_bf16 v[106:109], v[230:233], v[206:209], v[106:109]
	v_mfma_f32_16x16x32_bf16 v[98:101], v[238:241], v[206:209], v[98:101]
	v_mfma_f32_16x16x32_bf16 v[90:93], v[230:233], v[214:217], v[90:93]
	v_mfma_f32_16x16x32_bf16 v[82:85], v[238:241], v[214:217], v[82:85]
	v_mfma_f32_16x16x32_bf16 v[74:77], v[230:233], v[222:225], v[74:77]
	v_mfma_f32_16x16x32_bf16 v[66:69], v[238:241], v[222:225], v[66:69]
	v_mfma_f32_16x16x32_bf16 v[122:125], v[234:237], v[202:205], v[122:125]
	v_mfma_f32_16x16x32_bf16 v[114:117], v[242:245], v[202:205], v[114:117]
	v_mfma_f32_16x16x32_bf16 v[106:109], v[234:237], v[210:213], v[106:109]
	v_mfma_f32_16x16x32_bf16 v[98:101], v[242:245], v[210:213], v[98:101]
	v_mfma_f32_16x16x32_bf16 v[90:93], v[234:237], v[218:221], v[90:93]
	v_mfma_f32_16x16x32_bf16 v[82:85], v[242:245], v[218:221], v[82:85]
	v_mfma_f32_16x16x32_bf16 v[74:77], v[234:237], v[226:229], v[74:77]
	v_mfma_f32_16x16x32_bf16 v[66:69], v[242:245], v[226:229], v[66:69]
	s_setprio 0
	s_mov_b32 m0, s57
	v_lshl_add_u64 v[166:167], v[248:249], 0, s[10:11]
	s_barrier
	ds_read_b128 v[198:201], v181 offset:49152
	ds_read_b128 v[202:205], v181 offset:50176
	ds_read_b128 v[206:209], v181 offset:51200
	ds_read_b128 v[210:213], v181 offset:52224
	ds_read_b128 v[214:217], v181 offset:53248
	ds_read_b128 v[218:221], v181 offset:54272
	ds_read_b128 v[222:225], v181 offset:55296
	ds_read_b128 v[226:229], v181 offset:56320
	global_load_lds_dwordx4 v[166:167], off
	v_lshl_add_u64 v[134:135], v[134:135], 0, s[10:11]
	s_mov_b32 m0, s58
	s_nop 0
	global_load_lds_dwordx4 v[134:135], off
	s_barrier
	s_waitcnt lgkmcnt(0)
	s_setprio 1
	s_waitcnt lgkmcnt(0)
	v_mfma_f32_16x16x32_bf16 v[62:65], v[182:185], v[198:201], v[62:65]
	v_mfma_f32_16x16x32_bf16 v[54:57], v[190:193], v[198:201], v[54:57]
	v_mfma_f32_16x16x32_bf16 v[46:49], v[182:185], v[206:209], v[46:49]
	v_mfma_f32_16x16x32_bf16 v[38:41], v[190:193], v[206:209], v[38:41]
	v_mfma_f32_16x16x32_bf16 v[30:33], v[182:185], v[214:217], v[30:33]
	v_mfma_f32_16x16x32_bf16 v[22:25], v[190:193], v[214:217], v[22:25]
	v_mfma_f32_16x16x32_bf16 v[14:17], v[182:185], v[222:225], v[14:17]
	v_mfma_f32_16x16x32_bf16 v[6:9], v[190:193], v[222:225], v[6:9]
	v_mfma_f32_16x16x32_bf16 v[62:65], v[186:189], v[202:205], v[62:65]
	v_mfma_f32_16x16x32_bf16 v[54:57], v[194:197], v[202:205], v[54:57]
	v_mfma_f32_16x16x32_bf16 v[46:49], v[186:189], v[210:213], v[46:49]
	v_mfma_f32_16x16x32_bf16 v[38:41], v[194:197], v[210:213], v[38:41]
	v_mfma_f32_16x16x32_bf16 v[30:33], v[186:189], v[218:221], v[30:33]
	v_mfma_f32_16x16x32_bf16 v[22:25], v[194:197], v[218:221], v[22:25]
	v_mfma_f32_16x16x32_bf16 v[14:17], v[186:189], v[226:229], v[14:17]
	v_mfma_f32_16x16x32_bf16 v[6:9], v[194:197], v[226:229], v[6:9]
	s_setprio 0
	s_barrier
	s_add_u32 s26, s26, 0x80080
	s_addc_u32 s27, s27, 0
	s_add_i32 s52, s52, s6
	s_mov_b32 m0, s52
	s_nop 0
	global_load_lds_dwordx4 v0, s[26:27]
	s_add_i32 m0, s52, 0x2000
	s_nop 0
	global_load_lds_dwordx4 v138, s[26:27]
	s_waitcnt vmcnt(6)
	s_barrier
	s_setprio 1
	v_mfma_f32_16x16x32_bf16 v[58:61], v[230:233], v[198:201], v[58:61]
	v_mfma_f32_16x16x32_bf16 v[50:53], v[238:241], v[198:201], v[50:53]
	v_mfma_f32_16x16x32_bf16 v[42:45], v[230:233], v[206:209], v[42:45]
	v_mfma_f32_16x16x32_bf16 v[34:37], v[238:241], v[206:209], v[34:37]
	v_mfma_f32_16x16x32_bf16 v[26:29], v[230:233], v[214:217], v[26:29]
	v_mfma_f32_16x16x32_bf16 v[18:21], v[238:241], v[214:217], v[18:21]
	v_mfma_f32_16x16x32_bf16 v[10:13], v[230:233], v[222:225], v[10:13]
	v_mfma_f32_16x16x32_bf16 v[2:5], v[238:241], v[222:225], v[2:5]
	v_mfma_f32_16x16x32_bf16 v[58:61], v[234:237], v[202:205], v[58:61]
	v_mfma_f32_16x16x32_bf16 v[50:53], v[242:245], v[202:205], v[50:53]
	v_mfma_f32_16x16x32_bf16 v[42:45], v[234:237], v[210:213], v[42:45]
	v_mfma_f32_16x16x32_bf16 v[34:37], v[242:245], v[210:213], v[34:37]
	v_mfma_f32_16x16x32_bf16 v[26:29], v[234:237], v[218:221], v[26:29]
	v_mfma_f32_16x16x32_bf16 v[18:21], v[242:245], v[218:221], v[18:21]
	v_mfma_f32_16x16x32_bf16 v[10:13], v[234:237], v[226:229], v[10:13]
	v_mfma_f32_16x16x32_bf16 v[2:5], v[242:245], v[226:229], v[2:5]
	s_setprio 0
	s_add_i32 s66, s66, 2
	s_add_u32 s50, s50, 0x100
	s_addc_u32 s51, s51, 0
	s_add_u32 s64, s64, 0x100
	s_addc_u32 s65, s65, 0
	s_cmp_gt_u32 s66, 29
	s_barrier
	s_cbranch_scc0 .LBB0_108
	v_mul_f32_e32 v134, 0xbfb8aa3b, v126
	v_exp_f32_e32 v134, v134
	s_lshl_b32 s23, s61, 7
	s_or_b32 s23, s23, s56
	s_ashr_i32 s23, s23, 6
	v_add_f32_e32 v134, 1.0, v134
	v_rcp_f32_e32 v134, v134
	s_mul_i32 s26, s60, 0x58
	s_ashr_i32 s43, s23, 31
	s_mul_hi_i32 s27, s60, 0x58
	v_mul_f32_e32 v126, v126, v134
	v_mul_f32_e32 v122, v126, v122
	v_mul_f32_e32 v126, 0xbfb8aa3b, v118
	v_exp_f32_e32 v126, v126
	s_add_u32 s26, s26, s23
	s_addc_u32 s27, s27, s43
	s_lshl_b64 s[26:27], s[26:27], 15
	v_add_f32_e32 v126, 1.0, v126
	v_rcp_f32_e32 v126, v126
	v_lshl_add_u64 v[166:167], v[144:145], 0, s[26:27]
	s_and_b64 vcc, exec, s[38:39]
	s_mov_b32 s61, s22
	v_mul_f32_e32 v118, v118, v126
	v_mul_f32_e32 v126, v118, v114
	v_mul_f32_e32 v114, 0xbfb8aa3b, v127
	v_mul_f32_e32 v118, 0xbfb8aa3b, v119
	v_exp_f32_e32 v114, v114
	v_exp_f32_e32 v118, v118
	s_mov_b32 s60, s42
	s_mov_b64 s[26:27], s[24:25]
	v_add_f32_e32 v114, 1.0, v114
	v_add_f32_e32 v118, 1.0, v118
	v_rcp_f32_e32 v114, v114
	v_rcp_f32_e32 v118, v118
	s_mov_b64 s[50:51], s[48:49]
	v_readlane_b32 s70, v254, 38
	v_mul_f32_e32 v114, v127, v114
	v_mul_f32_e32 v118, v119, v118
	v_mul_f32_e32 v114, v114, v123
	v_mul_f32_e32 v123, v118, v115
	v_mul_f32_e32 v118, 0xbfb8aa3b, v120
	v_exp_f32_e32 v118, v118
	v_mul_f32_e32 v115, 0xbfb8aa3b, v128
	v_exp_f32_e32 v115, v115
	v_cvt_pk_bf16_f32 v114, v122, v114
	v_add_f32_e32 v118, 1.0, v118
	v_rcp_f32_e32 v118, v118
	v_add_f32_e32 v115, 1.0, v115
	v_rcp_f32_e32 v115, v115
	v_mul_f32_e32 v118, v120, v118
	v_mul_f32_e32 v120, v118, v116
	v_mul_f32_e32 v116, 0xbfb8aa3b, v129
	v_mul_f32_e32 v118, 0xbfb8aa3b, v121
	v_exp_f32_e32 v116, v116
	v_exp_f32_e32 v118, v118
	v_mul_f32_e32 v115, v128, v115
	v_mul_f32_e32 v115, v115, v124
	v_add_f32_e32 v116, 1.0, v116
	v_add_f32_e32 v118, 1.0, v118
	v_rcp_f32_e32 v116, v116
	v_rcp_f32_e32 v118, v118
	v_mul_f32_e32 v116, v129, v116
	v_mul_f32_e32 v118, v121, v118
	v_mul_f32_e32 v116, v116, v125
	v_mul_f32_e32 v117, v118, v117
	v_lshl_add_u64 v[118:119], v[166:167], 0, v[146:147]
	v_cvt_pk_bf16_f32 v115, v115, v116
	v_cvt_pk_bf16_f32 v116, v126, v123
	v_cvt_pk_bf16_f32 v117, v120, v117
	global_store_dwordx4 v[118:119], v[114:117], off
	s_nop 1
	v_mul_f32_e32 v114, 0xbfb8aa3b, v110
	v_exp_f32_e32 v114, v114
	s_nop 0
	v_add_f32_e32 v114, 1.0, v114
	v_rcp_f32_e32 v114, v114
	s_nop 0
	v_mul_f32_e32 v110, v110, v114
	v_mul_f32_e32 v106, v110, v106
	v_mul_f32_e32 v110, 0xbfb8aa3b, v102
	v_exp_f32_e32 v110, v110
	s_nop 0
	v_add_f32_e32 v110, 1.0, v110
	v_rcp_f32_e32 v110, v110
	s_nop 0
	v_mul_f32_e32 v102, v102, v110
	v_mul_f32_e32 v110, v102, v98
	v_mul_f32_e32 v98, 0xbfb8aa3b, v111
	v_mul_f32_e32 v102, 0xbfb8aa3b, v103
	v_exp_f32_e32 v98, v98
	v_exp_f32_e32 v102, v102
	v_add_f32_e32 v98, 1.0, v98
	v_add_f32_e32 v102, 1.0, v102
	v_rcp_f32_e32 v98, v98
	v_rcp_f32_e32 v102, v102
	v_mul_f32_e32 v98, v111, v98
	v_mul_f32_e32 v102, v103, v102
	v_mul_f32_e32 v98, v98, v107
	v_mul_f32_e32 v107, v102, v99
	v_mul_f32_e32 v102, 0xbfb8aa3b, v104
	v_exp_f32_e32 v102, v102
	v_mul_f32_e32 v99, 0xbfb8aa3b, v112
	v_exp_f32_e32 v99, v99
	v_cvt_pk_bf16_f32 v98, v106, v98
	v_add_f32_e32 v102, 1.0, v102
	v_rcp_f32_e32 v102, v102
	v_add_f32_e32 v99, 1.0, v99
	v_rcp_f32_e32 v99, v99
	v_mul_f32_e32 v102, v104, v102
	v_mul_f32_e32 v104, v102, v100
	v_mul_f32_e32 v100, 0xbfb8aa3b, v113
	v_mul_f32_e32 v102, 0xbfb8aa3b, v105
	v_exp_f32_e32 v100, v100
	v_exp_f32_e32 v102, v102
	v_mul_f32_e32 v99, v112, v99
	v_mul_f32_e32 v99, v99, v108
	v_add_f32_e32 v100, 1.0, v100
	v_add_f32_e32 v102, 1.0, v102
	v_rcp_f32_e32 v100, v100
	v_rcp_f32_e32 v102, v102
	v_mul_f32_e32 v100, v113, v100
	v_mul_f32_e32 v102, v105, v102
	v_mul_f32_e32 v100, v100, v109
	v_mul_f32_e32 v101, v102, v101
	v_lshl_add_u64 v[102:103], v[166:167], 0, v[148:149]
	v_cvt_pk_bf16_f32 v99, v99, v100
	v_cvt_pk_bf16_f32 v100, v110, v107
	v_cvt_pk_bf16_f32 v101, v104, v101
	global_store_dwordx4 v[102:103], v[98:101], off
	s_nop 1
	v_mul_f32_e32 v98, 0xbfb8aa3b, v94
	v_exp_f32_e32 v98, v98
	s_nop 0
	v_add_f32_e32 v98, 1.0, v98
	v_rcp_f32_e32 v98, v98
	s_nop 0
	v_mul_f32_e32 v94, v94, v98
	v_mul_f32_e32 v90, v94, v90
	v_mul_f32_e32 v94, 0xbfb8aa3b, v86
	v_exp_f32_e32 v94, v94
	s_nop 0
	v_add_f32_e32 v94, 1.0, v94
	v_rcp_f32_e32 v94, v94
	s_nop 0
	v_mul_f32_e32 v86, v86, v94
	v_mul_f32_e32 v94, v86, v82
	v_mul_f32_e32 v82, 0xbfb8aa3b, v95
	v_mul_f32_e32 v86, 0xbfb8aa3b, v87
	v_exp_f32_e32 v82, v82
	v_exp_f32_e32 v86, v86
	v_add_f32_e32 v82, 1.0, v82
	v_add_f32_e32 v86, 1.0, v86
	v_rcp_f32_e32 v82, v82
	v_rcp_f32_e32 v86, v86
	v_mul_f32_e32 v82, v95, v82
	v_mul_f32_e32 v86, v87, v86
	v_mul_f32_e32 v82, v82, v91
	v_mul_f32_e32 v91, v86, v83
	v_mul_f32_e32 v86, 0xbfb8aa3b, v88
	v_exp_f32_e32 v86, v86
	v_mul_f32_e32 v83, 0xbfb8aa3b, v96
	v_exp_f32_e32 v83, v83
	v_cvt_pk_bf16_f32 v82, v90, v82
	v_add_f32_e32 v86, 1.0, v86
	v_rcp_f32_e32 v86, v86
	v_add_f32_e32 v83, 1.0, v83
	v_rcp_f32_e32 v83, v83
	v_mul_f32_e32 v86, v88, v86
	v_mul_f32_e32 v88, v86, v84
	v_mul_f32_e32 v84, 0xbfb8aa3b, v97
	v_mul_f32_e32 v86, 0xbfb8aa3b, v89
	v_exp_f32_e32 v84, v84
	v_exp_f32_e32 v86, v86
	v_mul_f32_e32 v83, v96, v83
	v_mul_f32_e32 v83, v83, v92
	v_add_f32_e32 v84, 1.0, v84
	v_add_f32_e32 v86, 1.0, v86
	v_rcp_f32_e32 v84, v84
	v_rcp_f32_e32 v86, v86
	v_mul_f32_e32 v84, v97, v84
	v_mul_f32_e32 v86, v89, v86
	v_mul_f32_e32 v84, v84, v93
	v_mul_f32_e32 v85, v86, v85
	v_lshl_add_u64 v[86:87], v[166:167], 0, v[150:151]
	v_cvt_pk_bf16_f32 v83, v83, v84
	v_cvt_pk_bf16_f32 v84, v94, v91
	v_cvt_pk_bf16_f32 v85, v88, v85
	global_store_dwordx4 v[86:87], v[82:85], off
	s_nop 1
	v_mul_f32_e32 v82, 0xbfb8aa3b, v78
	v_exp_f32_e32 v82, v82
	s_nop 0
	v_add_f32_e32 v82, 1.0, v82
	v_rcp_f32_e32 v82, v82
	s_nop 0
	v_mul_f32_e32 v78, v78, v82
	v_mul_f32_e32 v74, v78, v74
	v_mul_f32_e32 v78, 0xbfb8aa3b, v70
	v_exp_f32_e32 v78, v78
	s_nop 0
	v_add_f32_e32 v78, 1.0, v78
	v_rcp_f32_e32 v78, v78
	s_nop 0
	v_mul_f32_e32 v70, v70, v78
	v_mul_f32_e32 v78, v70, v66
	v_mul_f32_e32 v66, 0xbfb8aa3b, v79
	v_mul_f32_e32 v70, 0xbfb8aa3b, v71
	v_exp_f32_e32 v66, v66
	v_exp_f32_e32 v70, v70
	v_add_f32_e32 v66, 1.0, v66
	v_add_f32_e32 v70, 1.0, v70
	v_rcp_f32_e32 v66, v66
	v_rcp_f32_e32 v70, v70
	v_mul_f32_e32 v66, v79, v66
	v_mul_f32_e32 v70, v71, v70
	v_mul_f32_e32 v66, v66, v75
	v_mul_f32_e32 v75, v70, v67
	v_mul_f32_e32 v70, 0xbfb8aa3b, v72
	v_exp_f32_e32 v70, v70
	v_mul_f32_e32 v67, 0xbfb8aa3b, v80
	v_exp_f32_e32 v67, v67
	v_cvt_pk_bf16_f32 v66, v74, v66
	v_add_f32_e32 v70, 1.0, v70
	v_rcp_f32_e32 v70, v70
	v_add_f32_e32 v67, 1.0, v67
	v_rcp_f32_e32 v67, v67
	v_mul_f32_e32 v70, v72, v70
	v_mul_f32_e32 v72, v70, v68
	v_mul_f32_e32 v68, 0xbfb8aa3b, v81
	v_mul_f32_e32 v70, 0xbfb8aa3b, v73
	v_exp_f32_e32 v68, v68
	v_exp_f32_e32 v70, v70
	v_mul_f32_e32 v67, v80, v67
	v_mul_f32_e32 v67, v67, v76
	v_add_f32_e32 v68, 1.0, v68
	v_add_f32_e32 v70, 1.0, v70
	v_rcp_f32_e32 v68, v68
	v_rcp_f32_e32 v70, v70
	v_mul_f32_e32 v68, v81, v68
	v_mul_f32_e32 v70, v73, v70
	v_mul_f32_e32 v68, v68, v77
	v_mul_f32_e32 v69, v70, v69
	v_lshl_add_u64 v[70:71], v[166:167], 0, v[152:153]
	v_cvt_pk_bf16_f32 v67, v67, v68
	v_cvt_pk_bf16_f32 v68, v78, v75
	v_cvt_pk_bf16_f32 v69, v72, v69
	global_store_dwordx4 v[70:71], v[66:69], off
	s_nop 1
	v_mul_f32_e32 v66, 0xbfb8aa3b, v62
	v_exp_f32_e32 v66, v66
	s_nop 0
	v_add_f32_e32 v66, 1.0, v66
	v_rcp_f32_e32 v66, v66
	s_nop 0
	v_mul_f32_e32 v62, v62, v66
	v_mul_f32_e32 v58, v62, v58
	v_mul_f32_e32 v62, 0xbfb8aa3b, v54
	v_exp_f32_e32 v62, v62
	s_nop 0
	v_add_f32_e32 v62, 1.0, v62
	v_rcp_f32_e32 v62, v62
	s_nop 0
	v_mul_f32_e32 v54, v54, v62
	v_mul_f32_e32 v62, v54, v50
	v_mul_f32_e32 v50, 0xbfb8aa3b, v63
	v_mul_f32_e32 v54, 0xbfb8aa3b, v55
	v_exp_f32_e32 v50, v50
	v_exp_f32_e32 v54, v54
	v_add_f32_e32 v50, 1.0, v50
	v_add_f32_e32 v54, 1.0, v54
	v_rcp_f32_e32 v50, v50
	v_rcp_f32_e32 v54, v54
	v_mul_f32_e32 v50, v63, v50
	v_mul_f32_e32 v54, v55, v54
	v_mul_f32_e32 v50, v50, v59
	v_mul_f32_e32 v59, v54, v51
	v_mul_f32_e32 v54, 0xbfb8aa3b, v56
	v_exp_f32_e32 v54, v54
	v_mul_f32_e32 v51, 0xbfb8aa3b, v64
	v_exp_f32_e32 v51, v51
	v_cvt_pk_bf16_f32 v50, v58, v50
	v_add_f32_e32 v54, 1.0, v54
	v_rcp_f32_e32 v54, v54
	v_add_f32_e32 v51, 1.0, v51
	v_rcp_f32_e32 v51, v51
	v_mul_f32_e32 v54, v56, v54
	v_mul_f32_e32 v56, v54, v52
	v_mul_f32_e32 v52, 0xbfb8aa3b, v65
	v_mul_f32_e32 v54, 0xbfb8aa3b, v57
	v_exp_f32_e32 v52, v52
	v_exp_f32_e32 v54, v54
	v_mul_f32_e32 v51, v64, v51
	v_mul_f32_e32 v51, v51, v60
	v_add_f32_e32 v52, 1.0, v52
	v_add_f32_e32 v54, 1.0, v54
	v_rcp_f32_e32 v52, v52
	v_rcp_f32_e32 v54, v54
	v_mul_f32_e32 v52, v65, v52
	v_mul_f32_e32 v54, v57, v54
	v_mul_f32_e32 v52, v52, v61
	v_mul_f32_e32 v53, v54, v53
	v_lshl_add_u64 v[54:55], v[166:167], 0, v[154:155]
	v_cvt_pk_bf16_f32 v51, v51, v52
	v_cvt_pk_bf16_f32 v52, v62, v59
	v_cvt_pk_bf16_f32 v53, v56, v53
	global_store_dwordx4 v[54:55], v[50:53], off
	s_nop 1
	v_mul_f32_e32 v50, 0xbfb8aa3b, v46
	v_exp_f32_e32 v50, v50
	s_nop 0
	v_add_f32_e32 v50, 1.0, v50
	v_rcp_f32_e32 v50, v50
	s_nop 0
	v_mul_f32_e32 v46, v46, v50
	v_mul_f32_e32 v42, v46, v42
	v_mul_f32_e32 v46, 0xbfb8aa3b, v38
	v_exp_f32_e32 v46, v46
	s_nop 0
	v_add_f32_e32 v46, 1.0, v46
	v_rcp_f32_e32 v46, v46
	s_nop 0
	v_mul_f32_e32 v38, v38, v46
	v_mul_f32_e32 v46, v38, v34
	v_mul_f32_e32 v34, 0xbfb8aa3b, v47
	v_mul_f32_e32 v38, 0xbfb8aa3b, v39
	v_exp_f32_e32 v34, v34
	v_exp_f32_e32 v38, v38
	v_add_f32_e32 v34, 1.0, v34
	v_add_f32_e32 v38, 1.0, v38
	v_rcp_f32_e32 v34, v34
	v_rcp_f32_e32 v38, v38
	v_mul_f32_e32 v34, v47, v34
	v_mul_f32_e32 v38, v39, v38
	v_mul_f32_e32 v34, v34, v43
	v_mul_f32_e32 v43, v38, v35
	v_mul_f32_e32 v38, 0xbfb8aa3b, v40
	v_exp_f32_e32 v38, v38
	v_mul_f32_e32 v35, 0xbfb8aa3b, v48
	v_exp_f32_e32 v35, v35
	v_cvt_pk_bf16_f32 v34, v42, v34
	v_add_f32_e32 v38, 1.0, v38
	v_rcp_f32_e32 v38, v38
	v_add_f32_e32 v35, 1.0, v35
	v_rcp_f32_e32 v35, v35
	v_mul_f32_e32 v38, v40, v38
	v_mul_f32_e32 v40, v38, v36
	v_mul_f32_e32 v36, 0xbfb8aa3b, v49
	v_mul_f32_e32 v38, 0xbfb8aa3b, v41
	v_exp_f32_e32 v36, v36
	v_exp_f32_e32 v38, v38
	v_mul_f32_e32 v35, v48, v35
	v_mul_f32_e32 v35, v35, v44
	v_add_f32_e32 v36, 1.0, v36
	v_add_f32_e32 v38, 1.0, v38
	v_rcp_f32_e32 v36, v36
	v_rcp_f32_e32 v38, v38
	v_mul_f32_e32 v36, v49, v36
	v_mul_f32_e32 v38, v41, v38
	v_mul_f32_e32 v36, v36, v45
	v_mul_f32_e32 v37, v38, v37
	v_lshl_add_u64 v[38:39], v[166:167], 0, v[156:157]
	v_cvt_pk_bf16_f32 v35, v35, v36
	v_cvt_pk_bf16_f32 v36, v46, v43
	v_cvt_pk_bf16_f32 v37, v40, v37
	global_store_dwordx4 v[38:39], v[34:37], off
	s_nop 1
	v_mul_f32_e32 v34, 0xbfb8aa3b, v30
	v_exp_f32_e32 v34, v34
	s_nop 0
	v_add_f32_e32 v34, 1.0, v34
	v_rcp_f32_e32 v34, v34
	s_nop 0
	v_mul_f32_e32 v30, v30, v34
	v_mul_f32_e32 v26, v30, v26
	v_mul_f32_e32 v30, 0xbfb8aa3b, v22
	v_exp_f32_e32 v30, v30
	s_nop 0
	v_add_f32_e32 v30, 1.0, v30
	v_rcp_f32_e32 v30, v30
	s_nop 0
	v_mul_f32_e32 v22, v22, v30
	v_mul_f32_e32 v30, v22, v18
	v_mul_f32_e32 v18, 0xbfb8aa3b, v31
	v_mul_f32_e32 v22, 0xbfb8aa3b, v23
	v_exp_f32_e32 v18, v18
	v_exp_f32_e32 v22, v22
	v_add_f32_e32 v18, 1.0, v18
	v_add_f32_e32 v22, 1.0, v22
	v_rcp_f32_e32 v18, v18
	v_rcp_f32_e32 v22, v22
	v_mul_f32_e32 v18, v31, v18
	v_mul_f32_e32 v22, v23, v22
	v_mul_f32_e32 v18, v18, v27
	v_mul_f32_e32 v27, v22, v19
	v_mul_f32_e32 v22, 0xbfb8aa3b, v24
	v_exp_f32_e32 v22, v22
	v_mul_f32_e32 v19, 0xbfb8aa3b, v32
	v_exp_f32_e32 v19, v19
	v_cvt_pk_bf16_f32 v18, v26, v18
	v_add_f32_e32 v22, 1.0, v22
	v_rcp_f32_e32 v22, v22
	v_add_f32_e32 v19, 1.0, v19
	v_rcp_f32_e32 v19, v19
	v_mul_f32_e32 v22, v24, v22
	v_mul_f32_e32 v24, v22, v20
	v_mul_f32_e32 v20, 0xbfb8aa3b, v33
	v_mul_f32_e32 v22, 0xbfb8aa3b, v25
	v_exp_f32_e32 v20, v20
	v_exp_f32_e32 v22, v22
	v_mul_f32_e32 v19, v32, v19
	v_mul_f32_e32 v19, v19, v28
	v_add_f32_e32 v20, 1.0, v20
	v_add_f32_e32 v22, 1.0, v22
	v_rcp_f32_e32 v20, v20
	v_rcp_f32_e32 v22, v22
	v_mul_f32_e32 v20, v33, v20
	v_mul_f32_e32 v22, v25, v22
	v_mul_f32_e32 v20, v20, v29
	v_mul_f32_e32 v21, v22, v21
	v_lshl_add_u64 v[22:23], v[166:167], 0, v[158:159]
	v_cvt_pk_bf16_f32 v19, v19, v20
	v_cvt_pk_bf16_f32 v20, v30, v27
	v_cvt_pk_bf16_f32 v21, v24, v21
	global_store_dwordx4 v[22:23], v[18:21], off
	s_nop 1
	v_mul_f32_e32 v18, 0xbfb8aa3b, v14
	v_exp_f32_e32 v18, v18
	s_nop 0
	v_add_f32_e32 v18, 1.0, v18
	v_rcp_f32_e32 v18, v18
	s_nop 0
	v_mul_f32_e32 v14, v14, v18
	v_mul_f32_e32 v10, v14, v10
	v_mul_f32_e32 v14, 0xbfb8aa3b, v6
	v_exp_f32_e32 v14, v14
	s_nop 0
	v_add_f32_e32 v14, 1.0, v14
	v_rcp_f32_e32 v14, v14
	s_nop 0
	v_mul_f32_e32 v6, v6, v14
	v_mul_f32_e32 v14, v6, v2
	v_mul_f32_e32 v2, 0xbfb8aa3b, v15
	v_mul_f32_e32 v6, 0xbfb8aa3b, v7
	v_exp_f32_e32 v2, v2
	v_exp_f32_e32 v6, v6
	v_add_f32_e32 v2, 1.0, v2
	v_add_f32_e32 v6, 1.0, v6
	v_rcp_f32_e32 v2, v2
	v_rcp_f32_e32 v6, v6
	v_mul_f32_e32 v2, v15, v2
	v_mul_f32_e32 v6, v7, v6
	v_mul_f32_e32 v2, v2, v11
	v_mul_f32_e32 v11, v6, v3
	v_mul_f32_e32 v6, 0xbfb8aa3b, v8
	v_exp_f32_e32 v6, v6
	v_mul_f32_e32 v3, 0xbfb8aa3b, v16
	v_exp_f32_e32 v3, v3
	v_cvt_pk_bf16_f32 v2, v10, v2
	v_add_f32_e32 v6, 1.0, v6
	v_rcp_f32_e32 v6, v6
	v_add_f32_e32 v3, 1.0, v3
	v_rcp_f32_e32 v3, v3
	v_mul_f32_e32 v6, v8, v6
	v_mul_f32_e32 v8, v6, v4
	v_mul_f32_e32 v4, 0xbfb8aa3b, v17
	v_mul_f32_e32 v6, 0xbfb8aa3b, v9
	v_exp_f32_e32 v4, v4
	v_exp_f32_e32 v6, v6
	v_mul_f32_e32 v3, v16, v3
	v_mul_f32_e32 v3, v3, v12
	v_add_f32_e32 v4, 1.0, v4
	v_add_f32_e32 v6, 1.0, v6
	v_rcp_f32_e32 v4, v4
	v_rcp_f32_e32 v6, v6
	v_mul_f32_e32 v4, v17, v4
	v_mul_f32_e32 v6, v9, v6
	v_mul_f32_e32 v4, v4, v13
	v_mul_f32_e32 v5, v6, v5
	v_lshl_add_u64 v[6:7], v[166:167], 0, v[160:161]
	v_cvt_pk_bf16_f32 v3, v3, v4
	v_cvt_pk_bf16_f32 v4, v14, v11
	v_cvt_pk_bf16_f32 v5, v8, v5
	global_store_dwordx4 v[6:7], v[2:5], off
	s_cbranch_vccz .LBB0_105
	s_waitcnt vmcnt(0)
	v_readlane_b32 s50, v254, 28
	v_readlane_b32 s56, v254, 30
	v_readlane_b32 s60, v254, 39
	s_cmpk_gt_u32 s4, 0xff
	v_readlane_b32 s51, v254, 29
	v_readlane_b32 s57, v254, 31
	v_readlane_b32 s61, v254, 40
	s_mov_b64 s[58:59], s[84:85]
	s_cbranch_scc1 .LBB0_112
	s_barrier

.LBB0_182:
	s_add_u32 s26, s38, 0x4000
	s_addc_u32 s27, s39, 0
	s_cmpk_eq_i32 s61, 0x54
	s_cselect_b32 s48, s0, s26
	s_cselect_b32 s49, s1, s27
	s_cselect_b32 s26, s24, s59
	s_cselect_b32 s27, s25, s60
	s_add_u32 s42, s48, 0x8000
	s_addc_u32 s43, s49, 0
	s_add_i32 s62, 0, 0x10000
	v_add_u32_e32 v134, s62, v155
	ds_read_b128 v[148:151], v134
	ds_read_b128 v[158:161], v134 offset:1024
	ds_read_b128 v[162:165], v134 offset:2048
	ds_read_b128 v[180:183], v134 offset:3072
	s_add_i32 m0, s7, 0xc000
	ds_read_b128 v[184:187], v157
	ds_read_b128 v[188:191], v157 offset:1024
	ds_read_b128 v[192:195], v157 offset:2048
	ds_read_b128 v[196:199], v157 offset:3072
	ds_read_b128 v[200:203], v157 offset:4096
	ds_read_b128 v[204:207], v157 offset:5120
	ds_read_b128 v[208:211], v157 offset:6144
	ds_read_b128 v[212:215], v157 offset:7168
	global_load_lds_dwordx4 v144, s[38:39]
	s_add_i32 m0, s7, 0xe000
	s_nop 0
	global_load_lds_dwordx4 v146, s[38:39]
	s_waitcnt lgkmcnt(8)
	s_barrier
	s_waitcnt lgkmcnt(0)
	s_setprio 1
	s_waitcnt lgkmcnt(0)
	v_mfma_f32_16x16x32_bf16 v[126:129], v[148:151], v[184:187], v[126:129]
	v_mfma_f32_16x16x32_bf16 v[122:125], v[162:165], v[184:187], v[122:125]
	v_mfma_f32_16x16x32_bf16 v[110:113], v[148:151], v[192:195], v[110:113]
	v_mfma_f32_16x16x32_bf16 v[106:109], v[162:165], v[192:195], v[106:109]
	v_mfma_f32_16x16x32_bf16 v[94:97], v[148:151], v[200:203], v[94:97]
	v_mfma_f32_16x16x32_bf16 v[90:93], v[162:165], v[200:203], v[90:93]
	v_mfma_f32_16x16x32_bf16 v[78:81], v[148:151], v[208:211], v[78:81]
	v_mfma_f32_16x16x32_bf16 v[74:77], v[162:165], v[208:211], v[74:77]
	v_mfma_f32_16x16x32_bf16 v[126:129], v[158:161], v[188:191], v[126:129]
	v_mfma_f32_16x16x32_bf16 v[122:125], v[180:183], v[188:191], v[122:125]
	v_mfma_f32_16x16x32_bf16 v[110:113], v[158:161], v[196:199], v[110:113]
	v_mfma_f32_16x16x32_bf16 v[106:109], v[180:183], v[196:199], v[106:109]
	v_mfma_f32_16x16x32_bf16 v[94:97], v[158:161], v[204:207], v[94:97]
	v_mfma_f32_16x16x32_bf16 v[90:93], v[180:183], v[204:207], v[90:93]
	v_mfma_f32_16x16x32_bf16 v[78:81], v[158:161], v[212:215], v[78:81]
	v_mfma_f32_16x16x32_bf16 v[74:77], v[180:183], v[212:215], v[74:77]
	s_setprio 0
	s_barrier
	s_add_i32 s64, 0, 0x14000
	v_add_u32_e32 v134, s64, v155
	s_add_i32 s62, s62, s6
	ds_read_b128 v[216:219], v134
	ds_read_b128 v[220:223], v134 offset:1024
	ds_read_b128 v[224:227], v134 offset:2048
	ds_read_b128 v[228:231], v134 offset:3072
	v_lshl_add_u64 v[134:135], s[26:27], 0, v[0:1]
	s_mov_b32 m0, s62
	v_lshl_add_u64 v[152:153], s[26:27], 0, v[138:139]
	global_load_lds_dwordx4 v[134:135], off
	s_add_i32 m0, s62, 0x2000
	s_nop 0
	global_load_lds_dwordx4 v[152:153], off
	s_barrier
	s_waitcnt lgkmcnt(0)
	s_setprio 1
	s_waitcnt lgkmcnt(0)
	v_mfma_f32_16x16x32_bf16 v[118:121], v[216:219], v[184:187], v[118:121]
	v_mfma_f32_16x16x32_bf16 v[114:117], v[224:227], v[184:187], v[114:117]
	v_mfma_f32_16x16x32_bf16 v[102:105], v[216:219], v[192:195], v[102:105]
	v_mfma_f32_16x16x32_bf16 v[98:101], v[224:227], v[192:195], v[98:101]
	v_mfma_f32_16x16x32_bf16 v[86:89], v[216:219], v[200:203], v[86:89]
	v_mfma_f32_16x16x32_bf16 v[82:85], v[224:227], v[200:203], v[82:85]
	v_mfma_f32_16x16x32_bf16 v[70:73], v[216:219], v[208:211], v[70:73]
	v_mfma_f32_16x16x32_bf16 v[66:69], v[224:227], v[208:211], v[66:69]
	v_mfma_f32_16x16x32_bf16 v[118:121], v[220:223], v[188:191], v[118:121]
	v_mfma_f32_16x16x32_bf16 v[114:117], v[228:231], v[188:191], v[114:117]
	v_mfma_f32_16x16x32_bf16 v[102:105], v[220:223], v[196:199], v[102:105]
	v_mfma_f32_16x16x32_bf16 v[98:101], v[228:231], v[196:199], v[98:101]
	v_mfma_f32_16x16x32_bf16 v[86:89], v[220:223], v[204:207], v[86:89]
	v_mfma_f32_16x16x32_bf16 v[82:85], v[228:231], v[204:207], v[82:85]
	v_mfma_f32_16x16x32_bf16 v[70:73], v[220:223], v[212:215], v[70:73]
	v_mfma_f32_16x16x32_bf16 v[66:69], v[228:231], v[212:215], v[66:69]
	s_setprio 0
	s_mov_b32 m0, s7
	s_barrier
	ds_read_b128 v[184:187], v157 offset:16384
	ds_read_b128 v[188:191], v157 offset:17408
	ds_read_b128 v[192:195], v157 offset:18432
	ds_read_b128 v[196:199], v157 offset:19456
	ds_read_b128 v[200:203], v157 offset:20480
	ds_read_b128 v[204:207], v157 offset:21504
	ds_read_b128 v[208:211], v157 offset:22528
	ds_read_b128 v[212:215], v157 offset:23552
	global_load_lds_dwordx4 v142, s[48:49]
	s_mov_b32 m0, s14
	s_nop 0
	global_load_lds_dwordx4 v140, s[48:49]
	s_barrier
	s_waitcnt lgkmcnt(0)
	s_setprio 1
	s_waitcnt lgkmcnt(0)
	v_mfma_f32_16x16x32_bf16 v[62:65], v[148:151], v[184:187], v[62:65]
	v_mfma_f32_16x16x32_bf16 v[58:61], v[162:165], v[184:187], v[58:61]
	v_mfma_f32_16x16x32_bf16 v[46:49], v[148:151], v[192:195], v[46:49]
	v_mfma_f32_16x16x32_bf16 v[42:45], v[162:165], v[192:195], v[42:45]
	v_mfma_f32_16x16x32_bf16 v[30:33], v[148:151], v[200:203], v[30:33]
	v_mfma_f32_16x16x32_bf16 v[26:29], v[162:165], v[200:203], v[26:29]
	v_mfma_f32_16x16x32_bf16 v[14:17], v[148:151], v[208:211], v[14:17]
	v_mfma_f32_16x16x32_bf16 v[10:13], v[162:165], v[208:211], v[10:13]
	v_mfma_f32_16x16x32_bf16 v[62:65], v[158:161], v[188:191], v[62:65]
	v_mfma_f32_16x16x32_bf16 v[58:61], v[180:183], v[188:191], v[58:61]
	v_mfma_f32_16x16x32_bf16 v[46:49], v[158:161], v[196:199], v[46:49]
	v_mfma_f32_16x16x32_bf16 v[42:45], v[180:183], v[196:199], v[42:45]
	v_mfma_f32_16x16x32_bf16 v[30:33], v[158:161], v[204:207], v[30:33]
	v_mfma_f32_16x16x32_bf16 v[26:29], v[180:183], v[204:207], v[26:29]
	v_mfma_f32_16x16x32_bf16 v[14:17], v[158:161], v[212:215], v[14:17]
	v_mfma_f32_16x16x32_bf16 v[10:13], v[180:183], v[212:215], v[10:13]
	s_setprio 0
	s_barrier
	s_add_u32 s62, s26, 0x160000
	s_addc_u32 s63, s27, 0
	s_add_i32 s64, s64, s6
	s_mov_b32 m0, s64
	s_nop 0
	global_load_lds_dwordx4 v0, s[62:63]
	s_add_i32 m0, s64, 0x2000
	s_nop 0
	global_load_lds_dwordx4 v138, s[62:63]
	s_waitcnt vmcnt(6)
	s_barrier
	s_setprio 1
	v_mfma_f32_16x16x32_bf16 v[54:57], v[216:219], v[184:187], v[54:57]
	v_mfma_f32_16x16x32_bf16 v[50:53], v[224:227], v[184:187], v[50:53]
	v_mfma_f32_16x16x32_bf16 v[38:41], v[216:219], v[192:195], v[38:41]
	v_mfma_f32_16x16x32_bf16 v[34:37], v[224:227], v[192:195], v[34:37]
	v_mfma_f32_16x16x32_bf16 v[22:25], v[216:219], v[200:203], v[22:25]
	v_mfma_f32_16x16x32_bf16 v[18:21], v[224:227], v[200:203], v[18:21]
	v_mfma_f32_16x16x32_bf16 v[6:9], v[216:219], v[208:211], v[6:9]
	v_mfma_f32_16x16x32_bf16 v[2:5], v[224:227], v[208:211], v[2:5]
	v_mfma_f32_16x16x32_bf16 v[54:57], v[220:223], v[188:191], v[54:57]
	v_mfma_f32_16x16x32_bf16 v[50:53], v[228:231], v[188:191], v[50:53]
	v_mfma_f32_16x16x32_bf16 v[38:41], v[220:223], v[196:199], v[38:41]
	v_mfma_f32_16x16x32_bf16 v[34:37], v[228:231], v[196:199], v[34:37]
	v_mfma_f32_16x16x32_bf16 v[22:25], v[220:223], v[204:207], v[22:25]
	v_mfma_f32_16x16x32_bf16 v[18:21], v[228:231], v[204:207], v[18:21]
	v_mfma_f32_16x16x32_bf16 v[6:9], v[220:223], v[212:215], v[6:9]
	v_mfma_f32_16x16x32_bf16 v[2:5], v[228:231], v[212:215], v[2:5]
	s_setprio 0
	s_add_i32 s62, 0, 0x18000
	v_add_u32_e32 v166, s62, v155
	s_barrier
	ds_read_b128 v[148:151], v166
	ds_read_b128 v[158:161], v166 offset:1024
	ds_read_b128 v[162:165], v166 offset:2048
	ds_read_b128 v[180:183], v166 offset:3072
	s_add_u32 s48, s48, 0x4000
	s_addc_u32 s49, s49, 0
	s_mov_b32 m0, s50
	ds_read_b128 v[184:187], v157 offset:32768
	ds_read_b128 v[188:191], v157 offset:33792
	ds_read_b128 v[192:195], v157 offset:34816
	ds_read_b128 v[196:199], v157 offset:35840
	ds_read_b128 v[200:203], v157 offset:36864
	ds_read_b128 v[204:207], v157 offset:37888
	ds_read_b128 v[208:211], v157 offset:38912
	ds_read_b128 v[212:215], v157 offset:39936
	global_load_lds_dwordx4 v142, s[48:49]
	s_mov_b32 m0, s51
	s_nop 0
	global_load_lds_dwordx4 v140, s[48:49]
	s_waitcnt lgkmcnt(8)
	s_barrier
	s_waitcnt lgkmcnt(0)
	s_setprio 1
	s_waitcnt lgkmcnt(0)
	v_mfma_f32_16x16x32_bf16 v[126:129], v[148:151], v[184:187], v[126:129]
	v_mfma_f32_16x16x32_bf16 v[122:125], v[162:165], v[184:187], v[122:125]
	v_mfma_f32_16x16x32_bf16 v[110:113], v[148:151], v[192:195], v[110:113]
	v_mfma_f32_16x16x32_bf16 v[106:109], v[162:165], v[192:195], v[106:109]
	v_mfma_f32_16x16x32_bf16 v[94:97], v[148:151], v[200:203], v[94:97]
	v_mfma_f32_16x16x32_bf16 v[90:93], v[162:165], v[200:203], v[90:93]
	v_mfma_f32_16x16x32_bf16 v[78:81], v[148:151], v[208:211], v[78:81]
	v_mfma_f32_16x16x32_bf16 v[74:77], v[162:165], v[208:211], v[74:77]
	v_mfma_f32_16x16x32_bf16 v[126:129], v[158:161], v[188:191], v[126:129]
	v_mfma_f32_16x16x32_bf16 v[122:125], v[180:183], v[188:191], v[122:125]
	v_mfma_f32_16x16x32_bf16 v[110:113], v[158:161], v[196:199], v[110:113]
	v_mfma_f32_16x16x32_bf16 v[106:109], v[180:183], v[196:199], v[106:109]
	v_mfma_f32_16x16x32_bf16 v[94:97], v[158:161], v[204:207], v[94:97]
	v_mfma_f32_16x16x32_bf16 v[90:93], v[180:183], v[204:207], v[90:93]
	v_mfma_f32_16x16x32_bf16 v[78:81], v[158:161], v[212:215], v[78:81]
	v_mfma_f32_16x16x32_bf16 v[74:77], v[180:183], v[212:215], v[74:77]
	s_setprio 0
	s_barrier
	s_add_i32 s48, 0, 0x1c000
	s_add_i32 s49, s62, s6
	v_add_u32_e32 v166, s48, v155
	v_lshl_add_u64 v[134:135], v[134:135], 0, s[10:11]
	s_mov_b32 m0, s49
	ds_read_b128 v[216:219], v166
	ds_read_b128 v[220:223], v166 offset:1024
	ds_read_b128 v[224:227], v166 offset:2048
	ds_read_b128 v[228:231], v166 offset:3072
	global_load_lds_dwordx4 v[134:135], off
	v_lshl_add_u64 v[134:135], v[152:153], 0, s[10:11]
	s_add_i32 m0, s49, 0x2000
	s_nop 0
	global_load_lds_dwordx4 v[134:135], off
	s_barrier
	s_waitcnt lgkmcnt(0)
	s_setprio 1
	s_waitcnt lgkmcnt(0)
	v_mfma_f32_16x16x32_bf16 v[118:121], v[216:219], v[184:187], v[118:121]
	v_mfma_f32_16x16x32_bf16 v[114:117], v[224:227], v[184:187], v[114:117]
	v_mfma_f32_16x16x32_bf16 v[102:105], v[216:219], v[192:195], v[102:105]
	v_mfma_f32_16x16x32_bf16 v[98:101], v[224:227], v[192:195], v[98:101]
	v_mfma_f32_16x16x32_bf16 v[86:89], v[216:219], v[200:203], v[86:89]
	v_mfma_f32_16x16x32_bf16 v[82:85], v[224:227], v[200:203], v[82:85]
	v_mfma_f32_16x16x32_bf16 v[70:73], v[216:219], v[208:211], v[70:73]
	v_mfma_f32_16x16x32_bf16 v[66:69], v[224:227], v[208:211], v[66:69]
	v_mfma_f32_16x16x32_bf16 v[118:121], v[220:223], v[188:191], v[118:121]
	v_mfma_f32_16x16x32_bf16 v[114:117], v[228:231], v[188:191], v[114:117]
	v_mfma_f32_16x16x32_bf16 v[102:105], v[220:223], v[196:199], v[102:105]
	v_mfma_f32_16x16x32_bf16 v[98:101], v[228:231], v[196:199], v[98:101]
	v_mfma_f32_16x16x32_bf16 v[86:89], v[220:223], v[204:207], v[86:89]
	v_mfma_f32_16x16x32_bf16 v[82:85], v[228:231], v[204:207], v[82:85]
	v_mfma_f32_16x16x32_bf16 v[70:73], v[220:223], v[212:215], v[70:73]
	v_mfma_f32_16x16x32_bf16 v[66:69], v[228:231], v[212:215], v[66:69]
	s_setprio 0
	s_mov_b32 m0, s52
	s_barrier
	ds_read_b128 v[184:187], v157 offset:49152
	ds_read_b128 v[188:191], v157 offset:50176
	ds_read_b128 v[192:195], v157 offset:51200
	ds_read_b128 v[196:199], v157 offset:52224
	ds_read_b128 v[200:203], v157 offset:53248
	ds_read_b128 v[204:207], v157 offset:54272
	ds_read_b128 v[208:211], v157 offset:55296
	ds_read_b128 v[212:215], v157 offset:56320
	global_load_lds_dwordx4 v142, s[42:43]
	s_mov_b32 m0, s53
	s_nop 0
	global_load_lds_dwordx4 v140, s[42:43]
	s_barrier
	s_waitcnt lgkmcnt(0)
	s_setprio 1
	s_waitcnt lgkmcnt(0)
	v_mfma_f32_16x16x32_bf16 v[62:65], v[148:151], v[184:187], v[62:65]
	v_mfma_f32_16x16x32_bf16 v[58:61], v[162:165], v[184:187], v[58:61]
	v_mfma_f32_16x16x32_bf16 v[46:49], v[148:151], v[192:195], v[46:49]
	v_mfma_f32_16x16x32_bf16 v[42:45], v[162:165], v[192:195], v[42:45]
	v_mfma_f32_16x16x32_bf16 v[30:33], v[148:151], v[200:203], v[30:33]
	v_mfma_f32_16x16x32_bf16 v[26:29], v[162:165], v[200:203], v[26:29]
	v_mfma_f32_16x16x32_bf16 v[14:17], v[148:151], v[208:211], v[14:17]
	v_mfma_f32_16x16x32_bf16 v[10:13], v[162:165], v[208:211], v[10:13]
	v_mfma_f32_16x16x32_bf16 v[62:65], v[158:161], v[188:191], v[62:65]
	v_mfma_f32_16x16x32_bf16 v[58:61], v[180:183], v[188:191], v[58:61]
	v_mfma_f32_16x16x32_bf16 v[46:49], v[158:161], v[196:199], v[46:49]
	v_mfma_f32_16x16x32_bf16 v[42:45], v[180:183], v[196:199], v[42:45]
	v_mfma_f32_16x16x32_bf16 v[30:33], v[158:161], v[204:207], v[30:33]
	v_mfma_f32_16x16x32_bf16 v[26:29], v[180:183], v[204:207], v[26:29]
	v_mfma_f32_16x16x32_bf16 v[14:17], v[158:161], v[212:215], v[14:17]
	v_mfma_f32_16x16x32_bf16 v[10:13], v[180:183], v[212:215], v[10:13]
	s_setprio 0
	s_barrier
	s_add_u32 s26, s26, 0x160080
	s_addc_u32 s27, s27, 0
	s_add_i32 s42, s48, s6
	s_mov_b32 m0, s42
	s_nop 0
	global_load_lds_dwordx4 v0, s[26:27]
	s_add_i32 m0, s42, 0x2000
	s_nop 0
	global_load_lds_dwordx4 v138, s[26:27]
	s_waitcnt vmcnt(6)
	s_barrier
	s_setprio 1
	v_mfma_f32_16x16x32_bf16 v[54:57], v[216:219], v[184:187], v[54:57]
	v_mfma_f32_16x16x32_bf16 v[50:53], v[224:227], v[184:187], v[50:53]
	v_mfma_f32_16x16x32_bf16 v[38:41], v[216:219], v[192:195], v[38:41]
	v_mfma_f32_16x16x32_bf16 v[34:37], v[224:227], v[192:195], v[34:37]
	v_mfma_f32_16x16x32_bf16 v[22:25], v[216:219], v[200:203], v[22:25]
	v_mfma_f32_16x16x32_bf16 v[18:21], v[224:227], v[200:203], v[18:21]
	v_mfma_f32_16x16x32_bf16 v[6:9], v[216:219], v[208:211], v[6:9]
	v_mfma_f32_16x16x32_bf16 v[2:5], v[224:227], v[208:211], v[2:5]
	v_mfma_f32_16x16x32_bf16 v[54:57], v[220:223], v[188:191], v[54:57]
	v_mfma_f32_16x16x32_bf16 v[50:53], v[228:231], v[188:191], v[50:53]
	v_mfma_f32_16x16x32_bf16 v[38:41], v[220:223], v[196:199], v[38:41]
	v_mfma_f32_16x16x32_bf16 v[34:37], v[228:231], v[196:199], v[34:37]
	v_mfma_f32_16x16x32_bf16 v[22:25], v[220:223], v[204:207], v[22:25]
	v_mfma_f32_16x16x32_bf16 v[18:21], v[228:231], v[204:207], v[18:21]
	v_mfma_f32_16x16x32_bf16 v[6:9], v[220:223], v[212:215], v[6:9]
	v_mfma_f32_16x16x32_bf16 v[2:5], v[228:231], v[212:215], v[2:5]
	s_setprio 0
	s_add_i32 s61, s61, 2
	s_add_u32 s59, s59, 0x100
	s_addc_u32 s60, s60, 0
	s_add_u32 s38, s38, 0x10000
	s_addc_u32 s39, s39, 0
	s_cmpk_gt_u32 s61, 0x55
	s_barrier
	s_cbranch_scc0 .LBB0_182
	v_lshl_add_u32 v152, s58, 8, v154
	v_lshl_or_b32 v150, s57, 8, v156
	v_ashrrev_i32_e32 v153, 31, v152
	v_ashrrev_i32_e32 v151, 31, v150
	v_lshlrev_b64 v[134:135], 11, v[152:153]
	v_lshl_add_u64 v[134:135], v[134:135], 0, v[150:151]
	v_lshlrev_b64 v[148:149], 2, v[134:135]
	v_lshl_add_u64 v[134:135], s[22:23], 0, v[148:149]
	v_lshl_add_u64 v[158:159], s[76:77], 0, v[148:149]
	v_readlane_b32 s62, v254, 34
	v_readlane_b32 s64, v254, 36
	v_readlane_b32 s60, v254, 39
	s_and_b64 vcc, exec, s[40:41]
	s_mov_b32 s57, s55
	s_mov_b32 s58, s56
	s_mov_b64 s[38:39], s[0:1]
	v_readlane_b32 s63, v254, 35
	v_readlane_b32 s65, v254, 37
	v_readlane_b32 s61, v254, 40
	v_mov_b64_e32 v[162:163], v[134:135]
	v_mov_b64_e32 v[152:153], v[158:159]
	global_load_dwordx4 v[180:183], v[162:163], off
	global_load_dwordx4 v[184:187], v[162:163], off offset:16
	global_load_dwordx4 v[188:191], v[162:163], off offset:512
	global_load_dwordx4 v[192:195], v[162:163], off offset:528
	s_mov_b64 s[26:27], 0x20000
	v_lshl_add_u64 v[164:165], v[134:135], 0, s[26:27]
	v_lshl_add_u64 v[160:161], v[158:159], 0, s[26:27]
	global_load_dwordx4 v[196:199], v[164:165], off
	global_load_dwordx4 v[200:203], v[164:165], off offset:16
	global_load_dwordx4 v[204:207], v[164:165], off offset:512
	global_load_dwordx4 v[208:211], v[164:165], off offset:528
	s_mov_b64 s[26:27], 0x40000
	v_lshl_add_u64 v[150:151], v[134:135], 0, s[26:27]
	v_lshl_add_u64 v[148:149], v[158:159], 0, s[26:27]
	global_load_dwordx4 v[212:215], v[150:151], off
	global_load_dwordx4 v[216:219], v[150:151], off offset:16
	global_load_dwordx4 v[220:223], v[150:151], off offset:512
	global_load_dwordx4 v[224:227], v[150:151], off offset:528
	s_waitcnt vmcnt(8)
	v_pk_fma_f32 v[126:127], v[126:127], 0.5, v[180:181] op_sel_hi:[1,0,1]
	v_pk_fma_f32 v[128:129], v[128:129], 0.5, v[182:183] op_sel_hi:[1,0,1]
	v_pk_fma_f32 v[122:123], v[122:123], 0.5, v[184:185] op_sel_hi:[1,0,1]
	v_pk_fma_f32 v[124:125], v[124:125], 0.5, v[186:187] op_sel_hi:[1,0,1]
	v_pk_fma_f32 v[118:119], v[118:119], 0.5, v[188:189] op_sel_hi:[1,0,1]
	v_pk_fma_f32 v[120:121], v[120:121], 0.5, v[190:191] op_sel_hi:[1,0,1]
	v_pk_fma_f32 v[114:115], v[114:115], 0.5, v[192:193] op_sel_hi:[1,0,1]
	v_pk_fma_f32 v[116:117], v[116:117], 0.5, v[194:195] op_sel_hi:[1,0,1]
	global_store_dwordx4 v[152:153], v[126:129], off
	global_store_dwordx4 v[152:153], v[122:125], off offset:16
	global_store_dwordx4 v[152:153], v[118:121], off offset:512
	global_store_dwordx4 v[152:153], v[114:117], off offset:528
	s_mov_b64 s[26:27], 0x60000
	v_lshl_add_u64 v[228:229], v[134:135], 0, s[26:27]
	v_lshl_add_u64 v[230:231], v[158:159], 0, s[26:27]
	global_load_dwordx4 v[180:183], v[228:229], off
	global_load_dwordx4 v[184:187], v[228:229], off offset:16
	global_load_dwordx4 v[188:191], v[228:229], off offset:512
	global_load_dwordx4 v[192:195], v[228:229], off offset:528
	s_waitcnt vmcnt(12)
	v_pk_fma_f32 v[110:111], v[110:111], 0.5, v[196:197] op_sel_hi:[1,0,1]
	v_pk_fma_f32 v[112:113], v[112:113], 0.5, v[198:199] op_sel_hi:[1,0,1]
	v_pk_fma_f32 v[106:107], v[106:107], 0.5, v[200:201] op_sel_hi:[1,0,1]
	v_pk_fma_f32 v[108:109], v[108:109], 0.5, v[202:203] op_sel_hi:[1,0,1]
	v_pk_fma_f32 v[102:103], v[102:103], 0.5, v[204:205] op_sel_hi:[1,0,1]
	v_pk_fma_f32 v[104:105], v[104:105], 0.5, v[206:207] op_sel_hi:[1,0,1]
	v_pk_fma_f32 v[98:99], v[98:99], 0.5, v[208:209] op_sel_hi:[1,0,1]
	v_pk_fma_f32 v[100:101], v[100:101], 0.5, v[210:211] op_sel_hi:[1,0,1]
	global_store_dwordx4 v[160:161], v[110:113], off
	global_store_dwordx4 v[160:161], v[106:109], off offset:16
	global_store_dwordx4 v[160:161], v[102:105], off offset:512
	global_store_dwordx4 v[160:161], v[98:101], off offset:528
	s_mov_b64 s[26:27], 0x100000
	v_lshl_add_u64 v[162:163], v[134:135], 0, s[26:27]
	v_lshl_add_u64 v[152:153], v[158:159], 0, s[26:27]
	global_load_dwordx4 v[196:199], v[162:163], off
	global_load_dwordx4 v[200:203], v[162:163], off offset:16
	global_load_dwordx4 v[204:207], v[162:163], off offset:512
	global_load_dwordx4 v[208:211], v[162:163], off offset:528
	s_waitcnt vmcnt(16)
	v_pk_fma_f32 v[94:95], v[94:95], 0.5, v[212:213] op_sel_hi:[1,0,1]
	v_pk_fma_f32 v[96:97], v[96:97], 0.5, v[214:215] op_sel_hi:[1,0,1]
	v_pk_fma_f32 v[90:91], v[90:91], 0.5, v[216:217] op_sel_hi:[1,0,1]
	v_pk_fma_f32 v[92:93], v[92:93], 0.5, v[218:219] op_sel_hi:[1,0,1]
	v_pk_fma_f32 v[86:87], v[86:87], 0.5, v[220:221] op_sel_hi:[1,0,1]
	v_pk_fma_f32 v[88:89], v[88:89], 0.5, v[222:223] op_sel_hi:[1,0,1]
	v_pk_fma_f32 v[82:83], v[82:83], 0.5, v[224:225] op_sel_hi:[1,0,1]
	v_pk_fma_f32 v[84:85], v[84:85], 0.5, v[226:227] op_sel_hi:[1,0,1]
	global_store_dwordx4 v[148:149], v[94:97], off
	global_store_dwordx4 v[148:149], v[90:93], off offset:16
	global_store_dwordx4 v[148:149], v[86:89], off offset:512
	global_store_dwordx4 v[148:149], v[82:85], off offset:528
	s_mov_b64 s[26:27], 0x120000
	v_lshl_add_u64 v[164:165], v[134:135], 0, s[26:27]
	v_lshl_add_u64 v[160:161], v[158:159], 0, s[26:27]
	global_load_dwordx4 v[212:215], v[164:165], off
	global_load_dwordx4 v[216:219], v[164:165], off offset:16
	global_load_dwordx4 v[220:223], v[164:165], off offset:512
	global_load_dwordx4 v[224:227], v[164:165], off offset:528
	s_waitcnt vmcnt(16)
	v_pk_fma_f32 v[78:79], v[78:79], 0.5, v[180:181] op_sel_hi:[1,0,1]
	v_pk_fma_f32 v[80:81], v[80:81], 0.5, v[182:183] op_sel_hi:[1,0,1]
	v_pk_fma_f32 v[74:75], v[74:75], 0.5, v[184:185] op_sel_hi:[1,0,1]
	v_pk_fma_f32 v[76:77], v[76:77], 0.5, v[186:187] op_sel_hi:[1,0,1]
	v_pk_fma_f32 v[70:71], v[70:71], 0.5, v[188:189] op_sel_hi:[1,0,1]
	v_pk_fma_f32 v[72:73], v[72:73], 0.5, v[190:191] op_sel_hi:[1,0,1]
	v_pk_fma_f32 v[66:67], v[66:67], 0.5, v[192:193] op_sel_hi:[1,0,1]
	v_pk_fma_f32 v[68:69], v[68:69], 0.5, v[194:195] op_sel_hi:[1,0,1]
	global_store_dwordx4 v[230:231], v[78:81], off
	global_store_dwordx4 v[230:231], v[74:77], off offset:16
	global_store_dwordx4 v[230:231], v[70:73], off offset:512
	global_store_dwordx4 v[230:231], v[66:69], off offset:528
	s_mov_b64 s[26:27], 0x140000
	v_lshl_add_u64 v[150:151], v[134:135], 0, s[26:27]
	v_lshl_add_u64 v[148:149], v[158:159], 0, s[26:27]
	global_load_dwordx4 v[180:183], v[150:151], off
	global_load_dwordx4 v[184:187], v[150:151], off offset:16
	global_load_dwordx4 v[188:191], v[150:151], off offset:512
	global_load_dwordx4 v[192:195], v[150:151], off offset:528
	s_waitcnt vmcnt(16)
	v_pk_fma_f32 v[62:63], v[62:63], 0.5, v[196:197] op_sel_hi:[1,0,1]
	v_pk_fma_f32 v[64:65], v[64:65], 0.5, v[198:199] op_sel_hi:[1,0,1]
	v_pk_fma_f32 v[58:59], v[58:59], 0.5, v[200:201] op_sel_hi:[1,0,1]
	v_pk_fma_f32 v[60:61], v[60:61], 0.5, v[202:203] op_sel_hi:[1,0,1]
	v_pk_fma_f32 v[54:55], v[54:55], 0.5, v[204:205] op_sel_hi:[1,0,1]
	v_pk_fma_f32 v[56:57], v[56:57], 0.5, v[206:207] op_sel_hi:[1,0,1]
	v_pk_fma_f32 v[50:51], v[50:51], 0.5, v[208:209] op_sel_hi:[1,0,1]
	v_pk_fma_f32 v[52:53], v[52:53], 0.5, v[210:211] op_sel_hi:[1,0,1]
	global_store_dwordx4 v[152:153], v[62:65], off
	global_store_dwordx4 v[152:153], v[58:61], off offset:16
	global_store_dwordx4 v[152:153], v[54:57], off offset:512
	global_store_dwordx4 v[152:153], v[50:53], off offset:528
	s_mov_b64 s[26:27], 0x160000
	v_lshl_add_u64 v[228:229], v[134:135], 0, s[26:27]
	v_lshl_add_u64 v[230:231], v[158:159], 0, s[26:27]
	global_load_dwordx4 v[196:199], v[228:229], off
	global_load_dwordx4 v[200:203], v[228:229], off offset:16
	global_load_dwordx4 v[204:207], v[228:229], off offset:512
	global_load_dwordx4 v[208:211], v[228:229], off offset:528
	s_waitcnt vmcnt(16)
	v_pk_fma_f32 v[46:47], v[46:47], 0.5, v[212:213] op_sel_hi:[1,0,1]
	v_pk_fma_f32 v[48:49], v[48:49], 0.5, v[214:215] op_sel_hi:[1,0,1]
	v_pk_fma_f32 v[42:43], v[42:43], 0.5, v[216:217] op_sel_hi:[1,0,1]
	v_pk_fma_f32 v[44:45], v[44:45], 0.5, v[218:219] op_sel_hi:[1,0,1]
	v_pk_fma_f32 v[38:39], v[38:39], 0.5, v[220:221] op_sel_hi:[1,0,1]
	v_pk_fma_f32 v[40:41], v[40:41], 0.5, v[222:223] op_sel_hi:[1,0,1]
	v_pk_fma_f32 v[34:35], v[34:35], 0.5, v[224:225] op_sel_hi:[1,0,1]
	v_pk_fma_f32 v[36:37], v[36:37], 0.5, v[226:227] op_sel_hi:[1,0,1]
	global_store_dwordx4 v[160:161], v[46:49], off
	global_store_dwordx4 v[160:161], v[42:45], off offset:16
	global_store_dwordx4 v[160:161], v[38:41], off offset:512
	global_store_dwordx4 v[160:161], v[34:37], off offset:528
	s_waitcnt vmcnt(12)
	v_pk_fma_f32 v[30:31], v[30:31], 0.5, v[180:181] op_sel_hi:[1,0,1]
	v_pk_fma_f32 v[32:33], v[32:33], 0.5, v[182:183] op_sel_hi:[1,0,1]
	v_pk_fma_f32 v[26:27], v[26:27], 0.5, v[184:185] op_sel_hi:[1,0,1]
	v_pk_fma_f32 v[28:29], v[28:29], 0.5, v[186:187] op_sel_hi:[1,0,1]
	v_pk_fma_f32 v[22:23], v[22:23], 0.5, v[188:189] op_sel_hi:[1,0,1]
	v_pk_fma_f32 v[24:25], v[24:25], 0.5, v[190:191] op_sel_hi:[1,0,1]
	v_pk_fma_f32 v[18:19], v[18:19], 0.5, v[192:193] op_sel_hi:[1,0,1]
	v_pk_fma_f32 v[20:21], v[20:21], 0.5, v[194:195] op_sel_hi:[1,0,1]
	global_store_dwordx4 v[148:149], v[30:33], off
	global_store_dwordx4 v[148:149], v[26:29], off offset:16
	global_store_dwordx4 v[148:149], v[22:25], off offset:512
	global_store_dwordx4 v[148:149], v[18:21], off offset:528
	s_waitcnt vmcnt(8)
	v_pk_fma_f32 v[14:15], v[14:15], 0.5, v[196:197] op_sel_hi:[1,0,1]
	v_pk_fma_f32 v[16:17], v[16:17], 0.5, v[198:199] op_sel_hi:[1,0,1]
	v_pk_fma_f32 v[10:11], v[10:11], 0.5, v[200:201] op_sel_hi:[1,0,1]
	v_pk_fma_f32 v[12:13], v[12:13], 0.5, v[202:203] op_sel_hi:[1,0,1]
	v_pk_fma_f32 v[6:7], v[6:7], 0.5, v[204:205] op_sel_hi:[1,0,1]
	v_pk_fma_f32 v[8:9], v[8:9], 0.5, v[206:207] op_sel_hi:[1,0,1]
	v_pk_fma_f32 v[2:3], v[2:3], 0.5, v[208:209] op_sel_hi:[1,0,1]
	v_pk_fma_f32 v[4:5], v[4:5], 0.5, v[210:211] op_sel_hi:[1,0,1]
	global_store_dwordx4 v[230:231], v[14:17], off
	global_store_dwordx4 v[230:231], v[10:13], off offset:16
	global_store_dwordx4 v[230:231], v[6:9], off offset:512
	global_store_dwordx4 v[230:231], v[2:5], off offset:528
	s_mov_b64 s[26:27], s[24:25]
	s_cbranch_vccz .LBB0_171
	s_waitcnt vmcnt(0)
	v_readlane_b32 s52, v254, 26
	v_readlane_b32 s56, v254, 30
	v_readlane_b32 s54, v254, 32
	s_cmpk_gt_u32 s4, 0xff
	v_readlane_b32 s53, v254, 27
	v_readlane_b32 s57, v254, 31
	v_readlane_b32 s55, v254, 33
	s_mov_b64 s[58:59], s[84:85]
	s_cbranch_scc1 .LBB0_186
	s_barrier

.LBB0_360:
	s_add_u32 s26, s42, 0xfff80080
	s_addc_u32 s27, s43, -1
	s_add_i32 s58, 0, 0x10000
	v_add_u32_e32 v134, s58, v153
	ds_read_b128 v[148:151], v134
	ds_read_b128 v[156:159], v134 offset:1024
	ds_read_b128 v[160:163], v134 offset:2048
	ds_read_b128 v[164:167], v134 offset:3072
	s_cmp_eq_u32 s57, 28
	s_cselect_b32 s45, s23, s27
	s_cselect_b32 s44, s53, s26
	s_cselect_b32 s27, s1, s56
	s_cselect_b32 s26, s54, s55
	s_add_i32 m0, s7, 0xc000
	ds_read_b128 v[180:183], v155
	ds_read_b128 v[184:187], v155 offset:1024
	ds_read_b128 v[188:191], v155 offset:2048
	ds_read_b128 v[192:195], v155 offset:3072
	ds_read_b128 v[196:199], v155 offset:4096
	ds_read_b128 v[200:203], v155 offset:5120
	ds_read_b128 v[204:207], v155 offset:6144
	ds_read_b128 v[208:211], v155 offset:7168
	global_load_lds_dwordx4 v144, s[42:43]
	s_add_i32 m0, s7, 0xe000
	s_nop 0
	global_load_lds_dwordx4 v146, s[42:43]
	s_waitcnt lgkmcnt(8)
	s_barrier
	s_waitcnt lgkmcnt(0)
	s_setprio 1
	s_waitcnt lgkmcnt(0)
	v_mfma_f32_16x16x32_bf16 v[126:129], v[148:151], v[180:183], v[126:129]
	v_mfma_f32_16x16x32_bf16 v[122:125], v[160:163], v[180:183], v[122:125]
	v_mfma_f32_16x16x32_bf16 v[118:121], v[148:151], v[188:191], v[118:121]
	v_mfma_f32_16x16x32_bf16 v[110:113], v[160:163], v[188:191], v[110:113]
	v_mfma_f32_16x16x32_bf16 v[102:105], v[148:151], v[196:199], v[102:105]
	v_mfma_f32_16x16x32_bf16 v[94:97], v[160:163], v[196:199], v[94:97]
	v_mfma_f32_16x16x32_bf16 v[86:89], v[148:151], v[204:207], v[86:89]
	v_mfma_f32_16x16x32_bf16 v[78:81], v[160:163], v[204:207], v[78:81]
	v_mfma_f32_16x16x32_bf16 v[126:129], v[156:159], v[184:187], v[126:129]
	v_mfma_f32_16x16x32_bf16 v[122:125], v[164:167], v[184:187], v[122:125]
	v_mfma_f32_16x16x32_bf16 v[118:121], v[156:159], v[192:195], v[118:121]
	v_mfma_f32_16x16x32_bf16 v[110:113], v[164:167], v[192:195], v[110:113]
	v_mfma_f32_16x16x32_bf16 v[102:105], v[156:159], v[200:203], v[102:105]
	v_mfma_f32_16x16x32_bf16 v[94:97], v[164:167], v[200:203], v[94:97]
	v_mfma_f32_16x16x32_bf16 v[86:89], v[156:159], v[208:211], v[86:89]
	v_mfma_f32_16x16x32_bf16 v[78:81], v[164:167], v[208:211], v[78:81]
	s_setprio 0
	s_barrier
	s_add_i32 s60, 0, 0x14000
	v_add_u32_e32 v134, s60, v153
	s_add_i32 s58, s58, s6
	ds_read_b128 v[212:215], v134
	ds_read_b128 v[216:219], v134 offset:1024
	ds_read_b128 v[220:223], v134 offset:2048
	ds_read_b128 v[224:227], v134 offset:3072
	v_lshl_add_u64 v[134:135], s[26:27], 0, v[0:1]
	s_mov_b32 m0, s58
	v_lshl_add_u64 v[228:229], s[26:27], 0, v[138:139]
	global_load_lds_dwordx4 v[134:135], off
	s_add_i32 m0, s58, 0x2000
	s_nop 0
	global_load_lds_dwordx4 v[228:229], off
	s_barrier
	s_waitcnt lgkmcnt(0)
	s_setprio 1
	s_waitcnt lgkmcnt(0)
	v_mfma_f32_16x16x32_bf16 v[114:117], v[212:215], v[180:183], v[114:117]
	v_mfma_f32_16x16x32_bf16 v[106:109], v[220:223], v[180:183], v[106:109]
	v_mfma_f32_16x16x32_bf16 v[98:101], v[212:215], v[188:191], v[98:101]
	v_mfma_f32_16x16x32_bf16 v[90:93], v[220:223], v[188:191], v[90:93]
	v_mfma_f32_16x16x32_bf16 v[82:85], v[212:215], v[196:199], v[82:85]
	v_mfma_f32_16x16x32_bf16 v[74:77], v[220:223], v[196:199], v[74:77]
	v_mfma_f32_16x16x32_bf16 v[70:73], v[212:215], v[204:207], v[70:73]
	v_mfma_f32_16x16x32_bf16 v[66:69], v[220:223], v[204:207], v[66:69]
	v_mfma_f32_16x16x32_bf16 v[114:117], v[216:219], v[184:187], v[114:117]
	v_mfma_f32_16x16x32_bf16 v[106:109], v[224:227], v[184:187], v[106:109]
	v_mfma_f32_16x16x32_bf16 v[98:101], v[216:219], v[192:195], v[98:101]
	v_mfma_f32_16x16x32_bf16 v[90:93], v[224:227], v[192:195], v[90:93]
	v_mfma_f32_16x16x32_bf16 v[82:85], v[216:219], v[200:203], v[82:85]
	v_mfma_f32_16x16x32_bf16 v[74:77], v[224:227], v[200:203], v[74:77]
	v_mfma_f32_16x16x32_bf16 v[70:73], v[216:219], v[208:211], v[70:73]
	v_mfma_f32_16x16x32_bf16 v[66:69], v[224:227], v[208:211], v[66:69]
	s_setprio 0
	s_mov_b32 m0, s7
	v_lshl_add_u64 v[230:231], s[44:45], 0, v[142:143]
	s_barrier
	ds_read_b128 v[180:183], v155 offset:16384
	ds_read_b128 v[184:187], v155 offset:17408
	ds_read_b128 v[188:191], v155 offset:18432
	ds_read_b128 v[192:195], v155 offset:19456
	ds_read_b128 v[196:199], v155 offset:20480
	ds_read_b128 v[200:203], v155 offset:21504
	ds_read_b128 v[204:207], v155 offset:22528
	ds_read_b128 v[208:211], v155 offset:23552
	global_load_lds_dwordx4 v[230:231], off
	v_lshl_add_u64 v[232:233], s[44:45], 0, v[140:141]
	s_mov_b32 m0, s14
	s_nop 0
	global_load_lds_dwordx4 v[232:233], off
	s_barrier
	s_waitcnt lgkmcnt(0)
	s_setprio 1
	s_waitcnt lgkmcnt(0)
	v_mfma_f32_16x16x32_bf16 v[62:65], v[148:151], v[180:183], v[62:65]
	v_mfma_f32_16x16x32_bf16 v[58:61], v[160:163], v[180:183], v[58:61]
	v_mfma_f32_16x16x32_bf16 v[54:57], v[148:151], v[188:191], v[54:57]
	v_mfma_f32_16x16x32_bf16 v[46:49], v[160:163], v[188:191], v[46:49]
	v_mfma_f32_16x16x32_bf16 v[38:41], v[148:151], v[196:199], v[38:41]
	v_mfma_f32_16x16x32_bf16 v[30:33], v[160:163], v[196:199], v[30:33]
	v_mfma_f32_16x16x32_bf16 v[22:25], v[148:151], v[204:207], v[22:25]
	v_mfma_f32_16x16x32_bf16 v[14:17], v[160:163], v[204:207], v[14:17]
	v_mfma_f32_16x16x32_bf16 v[62:65], v[156:159], v[184:187], v[62:65]
	v_mfma_f32_16x16x32_bf16 v[58:61], v[164:167], v[184:187], v[58:61]
	v_mfma_f32_16x16x32_bf16 v[54:57], v[156:159], v[192:195], v[54:57]
	v_mfma_f32_16x16x32_bf16 v[46:49], v[164:167], v[192:195], v[46:49]
	v_mfma_f32_16x16x32_bf16 v[38:41], v[156:159], v[200:203], v[38:41]
	v_mfma_f32_16x16x32_bf16 v[30:33], v[164:167], v[200:203], v[30:33]
	v_mfma_f32_16x16x32_bf16 v[22:25], v[156:159], v[208:211], v[22:25]
	v_mfma_f32_16x16x32_bf16 v[14:17], v[164:167], v[208:211], v[14:17]
	s_setprio 0
	s_barrier
	s_add_u32 s58, s26, 0x80000
	s_addc_u32 s59, s27, 0
	s_add_i32 s60, s60, s6
	s_mov_b32 m0, s60
	s_nop 0
	global_load_lds_dwordx4 v0, s[58:59]
	s_add_i32 m0, s60, 0x2000
	s_nop 0
	global_load_lds_dwordx4 v138, s[58:59]
	s_waitcnt vmcnt(6)
	s_barrier
	s_setprio 1
	v_mfma_f32_16x16x32_bf16 v[50:53], v[212:215], v[180:183], v[50:53]
	v_mfma_f32_16x16x32_bf16 v[42:45], v[220:223], v[180:183], v[42:45]
	v_mfma_f32_16x16x32_bf16 v[34:37], v[212:215], v[188:191], v[34:37]
	v_mfma_f32_16x16x32_bf16 v[26:29], v[220:223], v[188:191], v[26:29]
	v_mfma_f32_16x16x32_bf16 v[18:21], v[212:215], v[196:199], v[18:21]
	v_mfma_f32_16x16x32_bf16 v[10:13], v[220:223], v[196:199], v[10:13]
	v_mfma_f32_16x16x32_bf16 v[6:9], v[212:215], v[204:207], v[6:9]
	v_mfma_f32_16x16x32_bf16 v[2:5], v[220:223], v[204:207], v[2:5]
	v_mfma_f32_16x16x32_bf16 v[50:53], v[216:219], v[184:187], v[50:53]
	v_mfma_f32_16x16x32_bf16 v[42:45], v[224:227], v[184:187], v[42:45]
	v_mfma_f32_16x16x32_bf16 v[34:37], v[216:219], v[192:195], v[34:37]
	v_mfma_f32_16x16x32_bf16 v[26:29], v[224:227], v[192:195], v[26:29]
	v_mfma_f32_16x16x32_bf16 v[18:21], v[216:219], v[200:203], v[18:21]
	v_mfma_f32_16x16x32_bf16 v[10:13], v[224:227], v[200:203], v[10:13]
	v_mfma_f32_16x16x32_bf16 v[6:9], v[216:219], v[208:211], v[6:9]
	v_mfma_f32_16x16x32_bf16 v[2:5], v[224:227], v[208:211], v[2:5]
	s_setprio 0
	s_add_i32 s58, 0, 0x18000
	v_add_u32_e32 v164, s58, v153
	s_barrier
	ds_read_b128 v[148:151], v164
	ds_read_b128 v[156:159], v164 offset:1024
	ds_read_b128 v[160:163], v164 offset:2048
	ds_read_b128 v[164:167], v164 offset:3072
	s_add_u32 s44, s44, 0x80000
	s_addc_u32 s45, s45, 0
	s_mov_b32 m0, s46
	ds_read_b128 v[180:183], v155 offset:32768
	ds_read_b128 v[184:187], v155 offset:33792
	ds_read_b128 v[188:191], v155 offset:34816
	ds_read_b128 v[192:195], v155 offset:35840
	ds_read_b128 v[196:199], v155 offset:36864
	ds_read_b128 v[200:203], v155 offset:37888
	ds_read_b128 v[204:207], v155 offset:38912
	ds_read_b128 v[208:211], v155 offset:39936
	global_load_lds_dwordx4 v142, s[44:45]
	s_mov_b32 m0, s47
	s_nop 0
	global_load_lds_dwordx4 v140, s[44:45]
	s_waitcnt lgkmcnt(8)
	s_barrier
	s_waitcnt lgkmcnt(0)
	s_setprio 1
	s_waitcnt lgkmcnt(0)
	v_mfma_f32_16x16x32_bf16 v[126:129], v[148:151], v[180:183], v[126:129]
	v_mfma_f32_16x16x32_bf16 v[122:125], v[160:163], v[180:183], v[122:125]
	v_mfma_f32_16x16x32_bf16 v[118:121], v[148:151], v[188:191], v[118:121]
	v_mfma_f32_16x16x32_bf16 v[110:113], v[160:163], v[188:191], v[110:113]
	v_mfma_f32_16x16x32_bf16 v[102:105], v[148:151], v[196:199], v[102:105]
	v_mfma_f32_16x16x32_bf16 v[94:97], v[160:163], v[196:199], v[94:97]
	v_mfma_f32_16x16x32_bf16 v[86:89], v[148:151], v[204:207], v[86:89]
	v_mfma_f32_16x16x32_bf16 v[78:81], v[160:163], v[204:207], v[78:81]
	v_mfma_f32_16x16x32_bf16 v[126:129], v[156:159], v[184:187], v[126:129]
	v_mfma_f32_16x16x32_bf16 v[122:125], v[164:167], v[184:187], v[122:125]
	v_mfma_f32_16x16x32_bf16 v[118:121], v[156:159], v[192:195], v[118:121]
	v_mfma_f32_16x16x32_bf16 v[110:113], v[164:167], v[192:195], v[110:113]
	v_mfma_f32_16x16x32_bf16 v[102:105], v[156:159], v[200:203], v[102:105]
	v_mfma_f32_16x16x32_bf16 v[94:97], v[164:167], v[200:203], v[94:97]
	v_mfma_f32_16x16x32_bf16 v[86:89], v[156:159], v[208:211], v[86:89]
	v_mfma_f32_16x16x32_bf16 v[78:81], v[164:167], v[208:211], v[78:81]
	s_setprio 0
	s_barrier
	s_add_i32 s44, 0, 0x1c000
	s_add_i32 s45, s58, s6
	v_add_u32_e32 v224, s44, v153
	v_lshl_add_u64 v[134:135], v[134:135], 0, s[10:11]
	s_mov_b32 m0, s45
	ds_read_b128 v[212:215], v224
	ds_read_b128 v[216:219], v224 offset:1024
	ds_read_b128 v[220:223], v224 offset:2048
	ds_read_b128 v[224:227], v224 offset:3072
	global_load_lds_dwordx4 v[134:135], off
	v_lshl_add_u64 v[134:135], v[228:229], 0, s[10:11]
	s_add_i32 m0, s45, 0x2000
	s_nop 0
	global_load_lds_dwordx4 v[134:135], off
	s_barrier
	s_waitcnt lgkmcnt(0)
	s_setprio 1
	s_waitcnt lgkmcnt(0)
	v_mfma_f32_16x16x32_bf16 v[114:117], v[212:215], v[180:183], v[114:117]
	v_mfma_f32_16x16x32_bf16 v[106:109], v[220:223], v[180:183], v[106:109]
	v_mfma_f32_16x16x32_bf16 v[98:101], v[212:215], v[188:191], v[98:101]
	v_mfma_f32_16x16x32_bf16 v[90:93], v[220:223], v[188:191], v[90:93]
	v_mfma_f32_16x16x32_bf16 v[82:85], v[212:215], v[196:199], v[82:85]
	v_mfma_f32_16x16x32_bf16 v[74:77], v[220:223], v[196:199], v[74:77]
	v_mfma_f32_16x16x32_bf16 v[70:73], v[212:215], v[204:207], v[70:73]
	v_mfma_f32_16x16x32_bf16 v[66:69], v[220:223], v[204:207], v[66:69]
	v_mfma_f32_16x16x32_bf16 v[114:117], v[216:219], v[184:187], v[114:117]
	v_mfma_f32_16x16x32_bf16 v[106:109], v[224:227], v[184:187], v[106:109]
	v_mfma_f32_16x16x32_bf16 v[98:101], v[216:219], v[192:195], v[98:101]
	v_mfma_f32_16x16x32_bf16 v[90:93], v[224:227], v[192:195], v[90:93]
	v_mfma_f32_16x16x32_bf16 v[82:85], v[216:219], v[200:203], v[82:85]
	v_mfma_f32_16x16x32_bf16 v[74:77], v[224:227], v[200:203], v[74:77]
	v_mfma_f32_16x16x32_bf16 v[70:73], v[216:219], v[208:211], v[70:73]
	v_mfma_f32_16x16x32_bf16 v[66:69], v[224:227], v[208:211], v[66:69]
	s_setprio 0
	s_mov_b32 m0, s48
	v_lshl_add_u64 v[134:135], v[230:231], 0, s[10:11]
	s_barrier
	ds_read_b128 v[180:183], v155 offset:49152
	ds_read_b128 v[184:187], v155 offset:50176
	ds_read_b128 v[188:191], v155 offset:51200
	ds_read_b128 v[192:195], v155 offset:52224
	ds_read_b128 v[196:199], v155 offset:53248
	ds_read_b128 v[200:203], v155 offset:54272
	ds_read_b128 v[204:207], v155 offset:55296
	ds_read_b128 v[208:211], v155 offset:56320
	global_load_lds_dwordx4 v[134:135], off
	v_lshl_add_u64 v[134:135], v[232:233], 0, s[10:11]
	s_mov_b32 m0, s49
	s_nop 0
	global_load_lds_dwordx4 v[134:135], off
	s_barrier
	s_waitcnt lgkmcnt(0)
	s_setprio 1
	s_waitcnt lgkmcnt(0)
	v_mfma_f32_16x16x32_bf16 v[62:65], v[148:151], v[180:183], v[62:65]
	v_mfma_f32_16x16x32_bf16 v[58:61], v[160:163], v[180:183], v[58:61]
	v_mfma_f32_16x16x32_bf16 v[54:57], v[148:151], v[188:191], v[54:57]
	v_mfma_f32_16x16x32_bf16 v[46:49], v[160:163], v[188:191], v[46:49]
	v_mfma_f32_16x16x32_bf16 v[38:41], v[148:151], v[196:199], v[38:41]
	v_mfma_f32_16x16x32_bf16 v[30:33], v[160:163], v[196:199], v[30:33]
	v_mfma_f32_16x16x32_bf16 v[22:25], v[148:151], v[204:207], v[22:25]
	v_mfma_f32_16x16x32_bf16 v[14:17], v[160:163], v[204:207], v[14:17]
	v_mfma_f32_16x16x32_bf16 v[62:65], v[156:159], v[184:187], v[62:65]
	v_mfma_f32_16x16x32_bf16 v[58:61], v[164:167], v[184:187], v[58:61]
	v_mfma_f32_16x16x32_bf16 v[54:57], v[156:159], v[192:195], v[54:57]
	v_mfma_f32_16x16x32_bf16 v[46:49], v[164:167], v[192:195], v[46:49]
	v_mfma_f32_16x16x32_bf16 v[38:41], v[156:159], v[200:203], v[38:41]
	v_mfma_f32_16x16x32_bf16 v[30:33], v[164:167], v[200:203], v[30:33]
	v_mfma_f32_16x16x32_bf16 v[22:25], v[156:159], v[208:211], v[22:25]
	v_mfma_f32_16x16x32_bf16 v[14:17], v[164:167], v[208:211], v[14:17]
	s_setprio 0
	s_barrier
	s_add_u32 s26, s26, 0x80080
	s_addc_u32 s27, s27, 0
	s_add_i32 s44, s44, s6
	s_mov_b32 m0, s44
	s_nop 0
	global_load_lds_dwordx4 v0, s[26:27]
	s_add_i32 m0, s44, 0x2000
	s_nop 0
	global_load_lds_dwordx4 v138, s[26:27]
	s_waitcnt vmcnt(6)
	s_barrier
	s_setprio 1
	v_mfma_f32_16x16x32_bf16 v[50:53], v[212:215], v[180:183], v[50:53]
	v_mfma_f32_16x16x32_bf16 v[42:45], v[220:223], v[180:183], v[42:45]
	v_mfma_f32_16x16x32_bf16 v[34:37], v[212:215], v[188:191], v[34:37]
	v_mfma_f32_16x16x32_bf16 v[26:29], v[220:223], v[188:191], v[26:29]
	v_mfma_f32_16x16x32_bf16 v[18:21], v[212:215], v[196:199], v[18:21]
	v_mfma_f32_16x16x32_bf16 v[10:13], v[220:223], v[196:199], v[10:13]
	v_mfma_f32_16x16x32_bf16 v[6:9], v[212:215], v[204:207], v[6:9]
	v_mfma_f32_16x16x32_bf16 v[2:5], v[220:223], v[204:207], v[2:5]
	v_mfma_f32_16x16x32_bf16 v[50:53], v[216:219], v[184:187], v[50:53]
	v_mfma_f32_16x16x32_bf16 v[42:45], v[224:227], v[184:187], v[42:45]
	v_mfma_f32_16x16x32_bf16 v[34:37], v[216:219], v[192:195], v[34:37]
	v_mfma_f32_16x16x32_bf16 v[26:29], v[224:227], v[192:195], v[26:29]
	v_mfma_f32_16x16x32_bf16 v[18:21], v[216:219], v[200:203], v[18:21]
	v_mfma_f32_16x16x32_bf16 v[10:13], v[224:227], v[200:203], v[10:13]
	v_mfma_f32_16x16x32_bf16 v[6:9], v[216:219], v[208:211], v[6:9]
	v_mfma_f32_16x16x32_bf16 v[2:5], v[224:227], v[208:211], v[2:5]
	s_setprio 0
	s_add_i32 s57, s57, 2
	s_add_u32 s42, s42, 0x100
	s_addc_u32 s43, s43, 0
	s_add_u32 s55, s55, 0x100
	s_addc_u32 s56, s56, 0
	s_cmp_gt_u32 s57, 29
	s_barrier
	s_cbranch_scc0 .LBB0_360
	v_lshl_or_b32 v134, s51, 8, v154
	v_lshl_add_u32 v158, s52, 8, v152
	v_ashrrev_i32_e32 v135, 31, v134
	v_mov_b64_e32 v[148:149], s[88:89]
	v_mad_i64_i32 v[156:157], s[26:27], v158, s35, v[148:149]
	v_lshlrev_b64 v[150:151], 1, v[134:135]
	v_lshl_add_u64 v[134:135], v[156:157], 0, v[150:151]
	v_cvt_pk_bf16_f32 v126, v126, v127
	v_cvt_pk_bf16_f32 v127, v128, v129
	v_cvt_pk_bf16_f32 v128, v122, v123
	v_cvt_pk_bf16_f32 v129, v124, v125
	global_store_dwordx4 v[134:135], v[126:129], off
	v_cvt_pk_bf16_f32 v114, v114, v115
	v_cvt_pk_bf16_f32 v115, v116, v117
	v_cvt_pk_bf16_f32 v116, v106, v107
	v_or_b32_e32 v106, 16, v158
	v_mad_i64_i32 v[106:107], s[26:27], v106, s35, v[148:149]
	v_cvt_pk_bf16_f32 v117, v108, v109
	global_store_dwordx4 v[134:135], v[114:117], off offset:256
	s_and_b64 vcc, exec, s[40:41]
	s_mov_b32 s51, s0
	v_lshl_add_u64 v[114:115], v[106:107], 0, v[150:151]
	v_cvt_pk_bf16_f32 v106, v118, v119
	v_cvt_pk_bf16_f32 v107, v120, v121
	v_cvt_pk_bf16_f32 v108, v110, v111
	v_cvt_pk_bf16_f32 v109, v112, v113
	global_store_dwordx4 v[114:115], v[106:109], off
	v_cvt_pk_bf16_f32 v98, v98, v99
	v_cvt_pk_bf16_f32 v99, v100, v101
	v_cvt_pk_bf16_f32 v100, v90, v91
	v_or_b32_e32 v90, 32, v158
	v_mad_i64_i32 v[90:91], s[26:27], v90, s35, v[148:149]
	v_cvt_pk_bf16_f32 v101, v92, v93
	global_store_dwordx4 v[114:115], v[98:101], off offset:256
	s_mov_b32 s52, s22
	s_mov_b64 s[42:43], s[24:25]
	v_lshl_add_u64 v[98:99], v[90:91], 0, v[150:151]
	v_cvt_pk_bf16_f32 v90, v102, v103
	v_cvt_pk_bf16_f32 v91, v104, v105
	v_cvt_pk_bf16_f32 v92, v94, v95
	v_cvt_pk_bf16_f32 v93, v96, v97
	global_store_dwordx4 v[98:99], v[90:93], off
	v_cvt_pk_bf16_f32 v82, v82, v83
	v_cvt_pk_bf16_f32 v83, v84, v85
	v_cvt_pk_bf16_f32 v84, v74, v75
	v_or_b32_e32 v74, 48, v158
	v_mad_i64_i32 v[74:75], s[26:27], v74, s35, v[148:149]
	v_cvt_pk_bf16_f32 v85, v76, v77
	global_store_dwordx4 v[98:99], v[82:85], off offset:256
	s_nop 1
	v_lshl_add_u64 v[82:83], v[74:75], 0, v[150:151]
	v_cvt_pk_bf16_f32 v74, v86, v87
	v_cvt_pk_bf16_f32 v75, v88, v89
	v_cvt_pk_bf16_f32 v76, v78, v79
	v_cvt_pk_bf16_f32 v77, v80, v81
	global_store_dwordx4 v[82:83], v[74:77], off
	v_cvt_pk_bf16_f32 v70, v70, v71
	v_cvt_pk_bf16_f32 v71, v72, v73
	v_cvt_pk_bf16_f32 v72, v66, v67
	v_add_u32_e32 v66, 0x80, v158
	v_mad_i64_i32 v[66:67], s[26:27], v66, s35, v[148:149]
	v_lshl_add_u64 v[66:67], v[66:67], 0, v[150:151]
	v_cvt_pk_bf16_f32 v73, v68, v69
	global_store_dwordx4 v[82:83], v[70:73], off offset:256
	v_cvt_pk_bf16_f32 v62, v62, v63
	v_cvt_pk_bf16_f32 v63, v64, v65
	v_cvt_pk_bf16_f32 v64, v58, v59
	v_cvt_pk_bf16_f32 v65, v60, v61
	global_store_dwordx4 v[66:67], v[62:65], off
	v_cvt_pk_bf16_f32 v50, v50, v51
	v_cvt_pk_bf16_f32 v51, v52, v53
	v_cvt_pk_bf16_f32 v52, v42, v43
	v_add_u32_e32 v42, 0x90, v158
	v_mad_i64_i32 v[42:43], s[26:27], v42, s35, v[148:149]
	v_cvt_pk_bf16_f32 v53, v44, v45
	global_store_dwordx4 v[66:67], v[50:53], off offset:256
	s_nop 1
	v_lshl_add_u64 v[50:51], v[42:43], 0, v[150:151]
	v_cvt_pk_bf16_f32 v42, v54, v55
	v_cvt_pk_bf16_f32 v43, v56, v57
	v_cvt_pk_bf16_f32 v44, v46, v47
	v_cvt_pk_bf16_f32 v45, v48, v49
	global_store_dwordx4 v[50:51], v[42:45], off
	v_cvt_pk_bf16_f32 v34, v34, v35
	v_cvt_pk_bf16_f32 v35, v36, v37
	v_cvt_pk_bf16_f32 v36, v26, v27
	v_add_u32_e32 v26, 0xa0, v158
	v_mad_i64_i32 v[26:27], s[26:27], v26, s35, v[148:149]
	v_cvt_pk_bf16_f32 v37, v28, v29
	global_store_dwordx4 v[50:51], v[34:37], off offset:256
	s_nop 1
	v_lshl_add_u64 v[34:35], v[26:27], 0, v[150:151]
	v_cvt_pk_bf16_f32 v26, v38, v39
	v_cvt_pk_bf16_f32 v27, v40, v41
	v_cvt_pk_bf16_f32 v28, v30, v31
	v_cvt_pk_bf16_f32 v29, v32, v33
	global_store_dwordx4 v[34:35], v[26:29], off
	v_cvt_pk_bf16_f32 v18, v18, v19
	v_cvt_pk_bf16_f32 v19, v20, v21
	v_cvt_pk_bf16_f32 v20, v10, v11
	v_add_u32_e32 v10, 0xb0, v158
	v_mad_i64_i32 v[10:11], s[26:27], v10, s35, v[148:149]
	v_cvt_pk_bf16_f32 v21, v12, v13
	global_store_dwordx4 v[34:35], v[18:21], off offset:256
	s_mov_b64 s[26:27], s[38:39]
	s_nop 0
	v_lshl_add_u64 v[18:19], v[10:11], 0, v[150:151]
	v_cvt_pk_bf16_f32 v10, v22, v23
	v_cvt_pk_bf16_f32 v11, v24, v25
	v_cvt_pk_bf16_f32 v12, v14, v15
	v_cvt_pk_bf16_f32 v13, v16, v17
	global_store_dwordx4 v[18:19], v[10:13], off
	v_cvt_pk_bf16_f32 v6, v6, v7
	v_cvt_pk_bf16_f32 v7, v8, v9
	v_cvt_pk_bf16_f32 v8, v2, v3
	v_cvt_pk_bf16_f32 v9, v4, v5
	global_store_dwordx4 v[18:19], v[6:9], off offset:256
	s_cbranch_vccz .LBB0_357
	s_waitcnt vmcnt(0)
	v_readlane_b32 s52, v254, 26
	v_readlane_b32 s50, v254, 28
	s_cmpk_gt_u32 s4, 0xff
	v_readlane_b32 s53, v254, 27
	v_readlane_b32 s51, v254, 29
	s_cbranch_scc1 .LBB0_364
	s_barrier

.LBB0_627:
	s_add_u32 s26, s42, 0xfff80080
	s_addc_u32 s27, s43, -1
	s_add_i32 s58, 0, 0x10000
	v_add_u32_e32 v134, s58, v153
	ds_read_b128 v[148:151], v134
	ds_read_b128 v[156:159], v134 offset:1024
	ds_read_b128 v[160:163], v134 offset:2048
	ds_read_b128 v[164:167], v134 offset:3072
	s_cmp_eq_u32 s57, 28
	s_cselect_b32 s45, s23, s27
	s_cselect_b32 s44, s53, s26
	s_cselect_b32 s27, s1, s56
	s_cselect_b32 s26, s54, s55
	s_add_i32 m0, s7, 0xc000
	ds_read_b128 v[180:183], v155
	ds_read_b128 v[184:187], v155 offset:1024
	ds_read_b128 v[188:191], v155 offset:2048
	ds_read_b128 v[192:195], v155 offset:3072
	ds_read_b128 v[196:199], v155 offset:4096
	ds_read_b128 v[200:203], v155 offset:5120
	ds_read_b128 v[204:207], v155 offset:6144
	ds_read_b128 v[208:211], v155 offset:7168
	global_load_lds_dwordx4 v144, s[42:43]
	s_add_i32 m0, s7, 0xe000
	s_nop 0
	global_load_lds_dwordx4 v146, s[42:43]
	s_waitcnt lgkmcnt(8)
	s_barrier
	s_waitcnt lgkmcnt(0)
	s_setprio 1
	s_waitcnt lgkmcnt(0)
	v_mfma_f32_16x16x32_bf16 v[126:129], v[148:151], v[180:183], v[126:129]
	v_mfma_f32_16x16x32_bf16 v[122:125], v[160:163], v[180:183], v[122:125]
	v_mfma_f32_16x16x32_bf16 v[118:121], v[148:151], v[188:191], v[118:121]
	v_mfma_f32_16x16x32_bf16 v[110:113], v[160:163], v[188:191], v[110:113]
	v_mfma_f32_16x16x32_bf16 v[102:105], v[148:151], v[196:199], v[102:105]
	v_mfma_f32_16x16x32_bf16 v[94:97], v[160:163], v[196:199], v[94:97]
	v_mfma_f32_16x16x32_bf16 v[86:89], v[148:151], v[204:207], v[86:89]
	v_mfma_f32_16x16x32_bf16 v[78:81], v[160:163], v[204:207], v[78:81]
	v_mfma_f32_16x16x32_bf16 v[126:129], v[156:159], v[184:187], v[126:129]
	v_mfma_f32_16x16x32_bf16 v[122:125], v[164:167], v[184:187], v[122:125]
	v_mfma_f32_16x16x32_bf16 v[118:121], v[156:159], v[192:195], v[118:121]
	v_mfma_f32_16x16x32_bf16 v[110:113], v[164:167], v[192:195], v[110:113]
	v_mfma_f32_16x16x32_bf16 v[102:105], v[156:159], v[200:203], v[102:105]
	v_mfma_f32_16x16x32_bf16 v[94:97], v[164:167], v[200:203], v[94:97]
	v_mfma_f32_16x16x32_bf16 v[86:89], v[156:159], v[208:211], v[86:89]
	v_mfma_f32_16x16x32_bf16 v[78:81], v[164:167], v[208:211], v[78:81]
	s_setprio 0
	s_barrier
	s_add_i32 s60, 0, 0x14000
	v_add_u32_e32 v134, s60, v153
	s_add_i32 s58, s58, s6
	ds_read_b128 v[212:215], v134
	ds_read_b128 v[216:219], v134 offset:1024
	ds_read_b128 v[220:223], v134 offset:2048
	ds_read_b128 v[224:227], v134 offset:3072
	v_lshl_add_u64 v[134:135], s[26:27], 0, v[0:1]
	s_mov_b32 m0, s58
	v_lshl_add_u64 v[228:229], s[26:27], 0, v[138:139]
	global_load_lds_dwordx4 v[134:135], off
	s_add_i32 m0, s58, 0x2000
	s_nop 0
	global_load_lds_dwordx4 v[228:229], off
	s_barrier
	s_waitcnt lgkmcnt(0)
	s_setprio 1
	s_waitcnt lgkmcnt(0)
	v_mfma_f32_16x16x32_bf16 v[114:117], v[212:215], v[180:183], v[114:117]
	v_mfma_f32_16x16x32_bf16 v[106:109], v[220:223], v[180:183], v[106:109]
	v_mfma_f32_16x16x32_bf16 v[98:101], v[212:215], v[188:191], v[98:101]
	v_mfma_f32_16x16x32_bf16 v[90:93], v[220:223], v[188:191], v[90:93]
	v_mfma_f32_16x16x32_bf16 v[82:85], v[212:215], v[196:199], v[82:85]
	v_mfma_f32_16x16x32_bf16 v[74:77], v[220:223], v[196:199], v[74:77]
	v_mfma_f32_16x16x32_bf16 v[70:73], v[212:215], v[204:207], v[70:73]
	v_mfma_f32_16x16x32_bf16 v[66:69], v[220:223], v[204:207], v[66:69]
	v_mfma_f32_16x16x32_bf16 v[114:117], v[216:219], v[184:187], v[114:117]
	v_mfma_f32_16x16x32_bf16 v[106:109], v[224:227], v[184:187], v[106:109]
	v_mfma_f32_16x16x32_bf16 v[98:101], v[216:219], v[192:195], v[98:101]
	v_mfma_f32_16x16x32_bf16 v[90:93], v[224:227], v[192:195], v[90:93]
	v_mfma_f32_16x16x32_bf16 v[82:85], v[216:219], v[200:203], v[82:85]
	v_mfma_f32_16x16x32_bf16 v[74:77], v[224:227], v[200:203], v[74:77]
	v_mfma_f32_16x16x32_bf16 v[70:73], v[216:219], v[208:211], v[70:73]
	v_mfma_f32_16x16x32_bf16 v[66:69], v[224:227], v[208:211], v[66:69]
	s_setprio 0
	s_mov_b32 m0, s7
	v_lshl_add_u64 v[230:231], s[44:45], 0, v[142:143]
	s_barrier
	ds_read_b128 v[180:183], v155 offset:16384
	ds_read_b128 v[184:187], v155 offset:17408
	ds_read_b128 v[188:191], v155 offset:18432
	ds_read_b128 v[192:195], v155 offset:19456
	ds_read_b128 v[196:199], v155 offset:20480
	ds_read_b128 v[200:203], v155 offset:21504
	ds_read_b128 v[204:207], v155 offset:22528
	ds_read_b128 v[208:211], v155 offset:23552
	global_load_lds_dwordx4 v[230:231], off
	v_lshl_add_u64 v[232:233], s[44:45], 0, v[140:141]
	s_mov_b32 m0, s14
	s_nop 0
	global_load_lds_dwordx4 v[232:233], off
	s_barrier
	s_waitcnt lgkmcnt(0)
	s_setprio 1
	s_waitcnt lgkmcnt(0)
	v_mfma_f32_16x16x32_bf16 v[62:65], v[148:151], v[180:183], v[62:65]
	v_mfma_f32_16x16x32_bf16 v[58:61], v[160:163], v[180:183], v[58:61]
	v_mfma_f32_16x16x32_bf16 v[54:57], v[148:151], v[188:191], v[54:57]
	v_mfma_f32_16x16x32_bf16 v[46:49], v[160:163], v[188:191], v[46:49]
	v_mfma_f32_16x16x32_bf16 v[38:41], v[148:151], v[196:199], v[38:41]
	v_mfma_f32_16x16x32_bf16 v[30:33], v[160:163], v[196:199], v[30:33]
	v_mfma_f32_16x16x32_bf16 v[22:25], v[148:151], v[204:207], v[22:25]
	v_mfma_f32_16x16x32_bf16 v[14:17], v[160:163], v[204:207], v[14:17]
	v_mfma_f32_16x16x32_bf16 v[62:65], v[156:159], v[184:187], v[62:65]
	v_mfma_f32_16x16x32_bf16 v[58:61], v[164:167], v[184:187], v[58:61]
	v_mfma_f32_16x16x32_bf16 v[54:57], v[156:159], v[192:195], v[54:57]
	v_mfma_f32_16x16x32_bf16 v[46:49], v[164:167], v[192:195], v[46:49]
	v_mfma_f32_16x16x32_bf16 v[38:41], v[156:159], v[200:203], v[38:41]
	v_mfma_f32_16x16x32_bf16 v[30:33], v[164:167], v[200:203], v[30:33]
	v_mfma_f32_16x16x32_bf16 v[22:25], v[156:159], v[208:211], v[22:25]
	v_mfma_f32_16x16x32_bf16 v[14:17], v[164:167], v[208:211], v[14:17]
	s_setprio 0
	s_barrier
	s_add_u32 s58, s26, 0x80000
	s_addc_u32 s59, s27, 0
	s_add_i32 s60, s60, s6
	s_mov_b32 m0, s60
	s_nop 0
	global_load_lds_dwordx4 v0, s[58:59]
	s_add_i32 m0, s60, 0x2000
	s_nop 0
	global_load_lds_dwordx4 v138, s[58:59]
	s_waitcnt vmcnt(6)
	s_barrier
	s_setprio 1
	v_mfma_f32_16x16x32_bf16 v[50:53], v[212:215], v[180:183], v[50:53]
	v_mfma_f32_16x16x32_bf16 v[42:45], v[220:223], v[180:183], v[42:45]
	v_mfma_f32_16x16x32_bf16 v[34:37], v[212:215], v[188:191], v[34:37]
	v_mfma_f32_16x16x32_bf16 v[26:29], v[220:223], v[188:191], v[26:29]
	v_mfma_f32_16x16x32_bf16 v[18:21], v[212:215], v[196:199], v[18:21]
	v_mfma_f32_16x16x32_bf16 v[10:13], v[220:223], v[196:199], v[10:13]
	v_mfma_f32_16x16x32_bf16 v[6:9], v[212:215], v[204:207], v[6:9]
	v_mfma_f32_16x16x32_bf16 v[2:5], v[220:223], v[204:207], v[2:5]
	v_mfma_f32_16x16x32_bf16 v[50:53], v[216:219], v[184:187], v[50:53]
	v_mfma_f32_16x16x32_bf16 v[42:45], v[224:227], v[184:187], v[42:45]
	v_mfma_f32_16x16x32_bf16 v[34:37], v[216:219], v[192:195], v[34:37]
	v_mfma_f32_16x16x32_bf16 v[26:29], v[224:227], v[192:195], v[26:29]
	v_mfma_f32_16x16x32_bf16 v[18:21], v[216:219], v[200:203], v[18:21]
	v_mfma_f32_16x16x32_bf16 v[10:13], v[224:227], v[200:203], v[10:13]
	v_mfma_f32_16x16x32_bf16 v[6:9], v[216:219], v[208:211], v[6:9]
	v_mfma_f32_16x16x32_bf16 v[2:5], v[224:227], v[208:211], v[2:5]
	s_setprio 0
	s_add_i32 s58, 0, 0x18000
	v_add_u32_e32 v164, s58, v153
	s_barrier
	ds_read_b128 v[148:151], v164
	ds_read_b128 v[156:159], v164 offset:1024
	ds_read_b128 v[160:163], v164 offset:2048
	ds_read_b128 v[164:167], v164 offset:3072
	s_add_u32 s44, s44, 0x80000
	s_addc_u32 s45, s45, 0
	s_mov_b32 m0, s46
	ds_read_b128 v[180:183], v155 offset:32768
	ds_read_b128 v[184:187], v155 offset:33792
	ds_read_b128 v[188:191], v155 offset:34816
	ds_read_b128 v[192:195], v155 offset:35840
	ds_read_b128 v[196:199], v155 offset:36864
	ds_read_b128 v[200:203], v155 offset:37888
	ds_read_b128 v[204:207], v155 offset:38912
	ds_read_b128 v[208:211], v155 offset:39936
	global_load_lds_dwordx4 v142, s[44:45]
	s_mov_b32 m0, s47
	s_nop 0
	global_load_lds_dwordx4 v140, s[44:45]
	s_waitcnt lgkmcnt(8)
	s_barrier
	s_waitcnt lgkmcnt(0)
	s_setprio 1
	s_waitcnt lgkmcnt(0)
	v_mfma_f32_16x16x32_bf16 v[126:129], v[148:151], v[180:183], v[126:129]
	v_mfma_f32_16x16x32_bf16 v[122:125], v[160:163], v[180:183], v[122:125]
	v_mfma_f32_16x16x32_bf16 v[118:121], v[148:151], v[188:191], v[118:121]
	v_mfma_f32_16x16x32_bf16 v[110:113], v[160:163], v[188:191], v[110:113]
	v_mfma_f32_16x16x32_bf16 v[102:105], v[148:151], v[196:199], v[102:105]
	v_mfma_f32_16x16x32_bf16 v[94:97], v[160:163], v[196:199], v[94:97]
	v_mfma_f32_16x16x32_bf16 v[86:89], v[148:151], v[204:207], v[86:89]
	v_mfma_f32_16x16x32_bf16 v[78:81], v[160:163], v[204:207], v[78:81]
	v_mfma_f32_16x16x32_bf16 v[126:129], v[156:159], v[184:187], v[126:129]
	v_mfma_f32_16x16x32_bf16 v[122:125], v[164:167], v[184:187], v[122:125]
	v_mfma_f32_16x16x32_bf16 v[118:121], v[156:159], v[192:195], v[118:121]
	v_mfma_f32_16x16x32_bf16 v[110:113], v[164:167], v[192:195], v[110:113]
	v_mfma_f32_16x16x32_bf16 v[102:105], v[156:159], v[200:203], v[102:105]
	v_mfma_f32_16x16x32_bf16 v[94:97], v[164:167], v[200:203], v[94:97]
	v_mfma_f32_16x16x32_bf16 v[86:89], v[156:159], v[208:211], v[86:89]
	v_mfma_f32_16x16x32_bf16 v[78:81], v[164:167], v[208:211], v[78:81]
	s_setprio 0
	s_barrier
	s_add_i32 s44, 0, 0x1c000
	s_add_i32 s45, s58, s6
	v_add_u32_e32 v224, s44, v153
	v_lshl_add_u64 v[134:135], v[134:135], 0, s[10:11]
	s_mov_b32 m0, s45
	ds_read_b128 v[212:215], v224
	ds_read_b128 v[216:219], v224 offset:1024
	ds_read_b128 v[220:223], v224 offset:2048
	ds_read_b128 v[224:227], v224 offset:3072
	global_load_lds_dwordx4 v[134:135], off
	v_lshl_add_u64 v[134:135], v[228:229], 0, s[10:11]
	s_add_i32 m0, s45, 0x2000
	s_nop 0
	global_load_lds_dwordx4 v[134:135], off
	s_barrier
	s_waitcnt lgkmcnt(0)
	s_setprio 1
	s_waitcnt lgkmcnt(0)
	v_mfma_f32_16x16x32_bf16 v[114:117], v[212:215], v[180:183], v[114:117]
	v_mfma_f32_16x16x32_bf16 v[106:109], v[220:223], v[180:183], v[106:109]
	v_mfma_f32_16x16x32_bf16 v[98:101], v[212:215], v[188:191], v[98:101]
	v_mfma_f32_16x16x32_bf16 v[90:93], v[220:223], v[188:191], v[90:93]
	v_mfma_f32_16x16x32_bf16 v[82:85], v[212:215], v[196:199], v[82:85]
	v_mfma_f32_16x16x32_bf16 v[74:77], v[220:223], v[196:199], v[74:77]
	v_mfma_f32_16x16x32_bf16 v[70:73], v[212:215], v[204:207], v[70:73]
	v_mfma_f32_16x16x32_bf16 v[66:69], v[220:223], v[204:207], v[66:69]
	v_mfma_f32_16x16x32_bf16 v[114:117], v[216:219], v[184:187], v[114:117]
	v_mfma_f32_16x16x32_bf16 v[106:109], v[224:227], v[184:187], v[106:109]
	v_mfma_f32_16x16x32_bf16 v[98:101], v[216:219], v[192:195], v[98:101]
	v_mfma_f32_16x16x32_bf16 v[90:93], v[224:227], v[192:195], v[90:93]
	v_mfma_f32_16x16x32_bf16 v[82:85], v[216:219], v[200:203], v[82:85]
	v_mfma_f32_16x16x32_bf16 v[74:77], v[224:227], v[200:203], v[74:77]
	v_mfma_f32_16x16x32_bf16 v[70:73], v[216:219], v[208:211], v[70:73]
	v_mfma_f32_16x16x32_bf16 v[66:69], v[224:227], v[208:211], v[66:69]
	s_setprio 0
	s_mov_b32 m0, s48
	v_lshl_add_u64 v[134:135], v[230:231], 0, s[10:11]
	s_barrier
	ds_read_b128 v[180:183], v155 offset:49152
	ds_read_b128 v[184:187], v155 offset:50176
	ds_read_b128 v[188:191], v155 offset:51200
	ds_read_b128 v[192:195], v155 offset:52224
	ds_read_b128 v[196:199], v155 offset:53248
	ds_read_b128 v[200:203], v155 offset:54272
	ds_read_b128 v[204:207], v155 offset:55296
	ds_read_b128 v[208:211], v155 offset:56320
	global_load_lds_dwordx4 v[134:135], off
	v_lshl_add_u64 v[134:135], v[232:233], 0, s[10:11]
	s_mov_b32 m0, s49
	s_nop 0
	global_load_lds_dwordx4 v[134:135], off
	s_barrier
	s_waitcnt lgkmcnt(0)
	s_setprio 1
	s_waitcnt lgkmcnt(0)
	v_mfma_f32_16x16x32_bf16 v[62:65], v[148:151], v[180:183], v[62:65]
	v_mfma_f32_16x16x32_bf16 v[58:61], v[160:163], v[180:183], v[58:61]
	v_mfma_f32_16x16x32_bf16 v[54:57], v[148:151], v[188:191], v[54:57]
	v_mfma_f32_16x16x32_bf16 v[46:49], v[160:163], v[188:191], v[46:49]
	v_mfma_f32_16x16x32_bf16 v[38:41], v[148:151], v[196:199], v[38:41]
	v_mfma_f32_16x16x32_bf16 v[30:33], v[160:163], v[196:199], v[30:33]
	v_mfma_f32_16x16x32_bf16 v[22:25], v[148:151], v[204:207], v[22:25]
	v_mfma_f32_16x16x32_bf16 v[14:17], v[160:163], v[204:207], v[14:17]
	v_mfma_f32_16x16x32_bf16 v[62:65], v[156:159], v[184:187], v[62:65]
	v_mfma_f32_16x16x32_bf16 v[58:61], v[164:167], v[184:187], v[58:61]
	v_mfma_f32_16x16x32_bf16 v[54:57], v[156:159], v[192:195], v[54:57]
	v_mfma_f32_16x16x32_bf16 v[46:49], v[164:167], v[192:195], v[46:49]
	v_mfma_f32_16x16x32_bf16 v[38:41], v[156:159], v[200:203], v[38:41]
	v_mfma_f32_16x16x32_bf16 v[30:33], v[164:167], v[200:203], v[30:33]
	v_mfma_f32_16x16x32_bf16 v[22:25], v[156:159], v[208:211], v[22:25]
	v_mfma_f32_16x16x32_bf16 v[14:17], v[164:167], v[208:211], v[14:17]
	s_setprio 0
	s_barrier
	s_add_u32 s26, s26, 0x80080
	s_addc_u32 s27, s27, 0
	s_add_i32 s44, s44, s6
	s_mov_b32 m0, s44
	s_nop 0
	global_load_lds_dwordx4 v0, s[26:27]
	s_add_i32 m0, s44, 0x2000
	s_nop 0
	global_load_lds_dwordx4 v138, s[26:27]
	s_waitcnt vmcnt(6)
	s_barrier
	s_setprio 1
	v_mfma_f32_16x16x32_bf16 v[50:53], v[212:215], v[180:183], v[50:53]
	v_mfma_f32_16x16x32_bf16 v[42:45], v[220:223], v[180:183], v[42:45]
	v_mfma_f32_16x16x32_bf16 v[34:37], v[212:215], v[188:191], v[34:37]
	v_mfma_f32_16x16x32_bf16 v[26:29], v[220:223], v[188:191], v[26:29]
	v_mfma_f32_16x16x32_bf16 v[18:21], v[212:215], v[196:199], v[18:21]
	v_mfma_f32_16x16x32_bf16 v[10:13], v[220:223], v[196:199], v[10:13]
	v_mfma_f32_16x16x32_bf16 v[6:9], v[212:215], v[204:207], v[6:9]
	v_mfma_f32_16x16x32_bf16 v[2:5], v[220:223], v[204:207], v[2:5]
	v_mfma_f32_16x16x32_bf16 v[50:53], v[216:219], v[184:187], v[50:53]
	v_mfma_f32_16x16x32_bf16 v[42:45], v[224:227], v[184:187], v[42:45]
	v_mfma_f32_16x16x32_bf16 v[34:37], v[216:219], v[192:195], v[34:37]
	v_mfma_f32_16x16x32_bf16 v[26:29], v[224:227], v[192:195], v[26:29]
	v_mfma_f32_16x16x32_bf16 v[18:21], v[216:219], v[200:203], v[18:21]
	v_mfma_f32_16x16x32_bf16 v[10:13], v[224:227], v[200:203], v[10:13]
	v_mfma_f32_16x16x32_bf16 v[6:9], v[216:219], v[208:211], v[6:9]
	v_mfma_f32_16x16x32_bf16 v[2:5], v[224:227], v[208:211], v[2:5]
	s_setprio 0
	s_add_i32 s57, s57, 2
	s_add_u32 s42, s42, 0x100
	s_addc_u32 s43, s43, 0
	s_add_u32 s55, s55, 0x100
	s_addc_u32 s56, s56, 0
	s_cmp_gt_u32 s57, 29
	s_barrier
	s_cbranch_scc0 .LBB0_627
	v_lshl_or_b32 v134, s51, 8, v154
	v_lshl_add_u32 v158, s52, 8, v152
	v_ashrrev_i32_e32 v135, 31, v134
	v_mov_b64_e32 v[148:149], s[88:89]
	s_movk_i32 s1, 0x2200
	v_mad_i64_i32 v[156:157], s[26:27], v158, s1, v[148:149]
	v_lshlrev_b64 v[150:151], 1, v[134:135]
	v_lshl_add_u64 v[134:135], v[156:157], 0, v[150:151]
	v_cvt_pk_bf16_f32 v126, v126, v127
	v_cvt_pk_bf16_f32 v127, v128, v129
	v_cvt_pk_bf16_f32 v128, v122, v123
	v_cvt_pk_bf16_f32 v129, v124, v125
	global_store_dwordx4 v[134:135], v[126:129], off
	v_cvt_pk_bf16_f32 v114, v114, v115
	v_cvt_pk_bf16_f32 v115, v116, v117
	v_cvt_pk_bf16_f32 v116, v106, v107
	v_or_b32_e32 v106, 16, v158
	v_mad_i64_i32 v[106:107], s[26:27], v106, s1, v[148:149]
	v_cvt_pk_bf16_f32 v117, v108, v109
	global_store_dwordx4 v[134:135], v[114:117], off offset:256
	s_and_b64 vcc, exec, s[40:41]
	s_mov_b32 s51, s0
	v_lshl_add_u64 v[114:115], v[106:107], 0, v[150:151]
	v_cvt_pk_bf16_f32 v106, v118, v119
	v_cvt_pk_bf16_f32 v107, v120, v121
	v_cvt_pk_bf16_f32 v108, v110, v111
	v_cvt_pk_bf16_f32 v109, v112, v113
	global_store_dwordx4 v[114:115], v[106:109], off
	v_cvt_pk_bf16_f32 v98, v98, v99
	v_cvt_pk_bf16_f32 v99, v100, v101
	v_cvt_pk_bf16_f32 v100, v90, v91
	v_or_b32_e32 v90, 32, v158
	v_mad_i64_i32 v[90:91], s[26:27], v90, s1, v[148:149]
	v_cvt_pk_bf16_f32 v101, v92, v93
	global_store_dwordx4 v[114:115], v[98:101], off offset:256
	s_mov_b32 s52, s22
	s_mov_b64 s[42:43], s[24:25]
	v_lshl_add_u64 v[98:99], v[90:91], 0, v[150:151]
	v_cvt_pk_bf16_f32 v90, v102, v103
	v_cvt_pk_bf16_f32 v91, v104, v105
	v_cvt_pk_bf16_f32 v92, v94, v95
	v_cvt_pk_bf16_f32 v93, v96, v97
	global_store_dwordx4 v[98:99], v[90:93], off
	v_cvt_pk_bf16_f32 v82, v82, v83
	v_cvt_pk_bf16_f32 v83, v84, v85
	v_cvt_pk_bf16_f32 v84, v74, v75
	v_or_b32_e32 v74, 48, v158
	v_mad_i64_i32 v[74:75], s[26:27], v74, s1, v[148:149]
	v_cvt_pk_bf16_f32 v85, v76, v77
	global_store_dwordx4 v[98:99], v[82:85], off offset:256
	s_nop 1
	v_lshl_add_u64 v[82:83], v[74:75], 0, v[150:151]
	v_cvt_pk_bf16_f32 v74, v86, v87
	v_cvt_pk_bf16_f32 v75, v88, v89
	v_cvt_pk_bf16_f32 v76, v78, v79
	v_cvt_pk_bf16_f32 v77, v80, v81
	global_store_dwordx4 v[82:83], v[74:77], off
	v_cvt_pk_bf16_f32 v70, v70, v71
	v_cvt_pk_bf16_f32 v71, v72, v73
	v_cvt_pk_bf16_f32 v72, v66, v67
	v_add_u32_e32 v66, 0x80, v158
	v_mad_i64_i32 v[66:67], s[26:27], v66, s1, v[148:149]
	v_lshl_add_u64 v[66:67], v[66:67], 0, v[150:151]
	v_cvt_pk_bf16_f32 v73, v68, v69
	global_store_dwordx4 v[82:83], v[70:73], off offset:256
	v_cvt_pk_bf16_f32 v62, v62, v63
	v_cvt_pk_bf16_f32 v63, v64, v65
	v_cvt_pk_bf16_f32 v64, v58, v59
	v_cvt_pk_bf16_f32 v65, v60, v61
	global_store_dwordx4 v[66:67], v[62:65], off
	v_cvt_pk_bf16_f32 v50, v50, v51
	v_cvt_pk_bf16_f32 v51, v52, v53
	v_cvt_pk_bf16_f32 v52, v42, v43
	v_add_u32_e32 v42, 0x90, v158
	v_mad_i64_i32 v[42:43], s[26:27], v42, s1, v[148:149]
	v_cvt_pk_bf16_f32 v53, v44, v45
	global_store_dwordx4 v[66:67], v[50:53], off offset:256
	s_nop 1
	v_lshl_add_u64 v[50:51], v[42:43], 0, v[150:151]
	v_cvt_pk_bf16_f32 v42, v54, v55
	v_cvt_pk_bf16_f32 v43, v56, v57
	v_cvt_pk_bf16_f32 v44, v46, v47
	v_cvt_pk_bf16_f32 v45, v48, v49
	global_store_dwordx4 v[50:51], v[42:45], off
	v_cvt_pk_bf16_f32 v34, v34, v35
	v_cvt_pk_bf16_f32 v35, v36, v37
	v_cvt_pk_bf16_f32 v36, v26, v27
	v_add_u32_e32 v26, 0xa0, v158
	v_mad_i64_i32 v[26:27], s[26:27], v26, s1, v[148:149]
	v_cvt_pk_bf16_f32 v37, v28, v29
	global_store_dwordx4 v[50:51], v[34:37], off offset:256
	s_nop 1
	v_lshl_add_u64 v[34:35], v[26:27], 0, v[150:151]
	v_cvt_pk_bf16_f32 v26, v38, v39
	v_cvt_pk_bf16_f32 v27, v40, v41
	v_cvt_pk_bf16_f32 v28, v30, v31
	v_cvt_pk_bf16_f32 v29, v32, v33
	global_store_dwordx4 v[34:35], v[26:29], off
	v_cvt_pk_bf16_f32 v18, v18, v19
	v_cvt_pk_bf16_f32 v19, v20, v21
	v_cvt_pk_bf16_f32 v20, v10, v11
	v_add_u32_e32 v10, 0xb0, v158
	v_mad_i64_i32 v[10:11], s[26:27], v10, s1, v[148:149]
	v_cvt_pk_bf16_f32 v21, v12, v13
	global_store_dwordx4 v[34:35], v[18:21], off offset:256
	s_mov_b64 s[26:27], s[38:39]
	s_nop 0
	v_lshl_add_u64 v[18:19], v[10:11], 0, v[150:151]
	v_cvt_pk_bf16_f32 v10, v22, v23
	v_cvt_pk_bf16_f32 v11, v24, v25
	v_cvt_pk_bf16_f32 v12, v14, v15
	v_cvt_pk_bf16_f32 v13, v16, v17
	global_store_dwordx4 v[18:19], v[10:13], off
	v_cvt_pk_bf16_f32 v6, v6, v7
	v_cvt_pk_bf16_f32 v7, v8, v9
	v_cvt_pk_bf16_f32 v8, v2, v3
	v_cvt_pk_bf16_f32 v9, v4, v5
	global_store_dwordx4 v[18:19], v[6:9], off offset:256
	s_cbranch_vccz .LBB0_624
	s_waitcnt vmcnt(0)
	v_readlane_b32 s52, v254, 26
	v_readlane_b32 s50, v254, 28
	s_cmpk_gt_u32 s4, 0xff
	v_readlane_b32 s53, v254, 27
	v_readlane_b32 s51, v254, 29
	s_cbranch_scc1 .LBB0_631
	s_barrier

.LBB0_1034:
	s_add_u32 s26, s42, 0xfff80080
	s_addc_u32 s27, s43, -1
	s_add_i32 s58, 0, 0x10000
	v_add_u32_e32 v134, s58, v155
	ds_read_b128 v[148:151], v134
	ds_read_b128 v[158:161], v134 offset:1024
	ds_read_b128 v[162:165], v134 offset:2048
	ds_read_b128 v[180:183], v134 offset:3072
	s_cmp_eq_u32 s57, 28
	s_cselect_b32 s45, s23, s27
	s_cselect_b32 s44, s53, s26
	s_cselect_b32 s27, s1, s56
	s_cselect_b32 s26, s54, s55
	s_add_i32 m0, s7, 0xc000
	ds_read_b128 v[184:187], v157
	ds_read_b128 v[188:191], v157 offset:1024
	ds_read_b128 v[192:195], v157 offset:2048
	ds_read_b128 v[196:199], v157 offset:3072
	ds_read_b128 v[200:203], v157 offset:4096
	ds_read_b128 v[204:207], v157 offset:5120
	ds_read_b128 v[208:211], v157 offset:6144
	ds_read_b128 v[212:215], v157 offset:7168
	global_load_lds_dwordx4 v144, s[42:43]
	s_add_i32 m0, s7, 0xe000
	s_nop 0
	global_load_lds_dwordx4 v146, s[42:43]
	s_waitcnt lgkmcnt(8)
	s_barrier
	s_waitcnt lgkmcnt(0)
	s_setprio 1
	s_waitcnt lgkmcnt(0)
	v_mfma_f32_16x16x32_bf16 v[126:129], v[148:151], v[184:187], v[126:129]
	v_mfma_f32_16x16x32_bf16 v[122:125], v[162:165], v[184:187], v[122:125]
	v_mfma_f32_16x16x32_bf16 v[110:113], v[148:151], v[192:195], v[110:113]
	v_mfma_f32_16x16x32_bf16 v[106:109], v[162:165], v[192:195], v[106:109]
	v_mfma_f32_16x16x32_bf16 v[94:97], v[148:151], v[200:203], v[94:97]
	v_mfma_f32_16x16x32_bf16 v[90:93], v[162:165], v[200:203], v[90:93]
	v_mfma_f32_16x16x32_bf16 v[78:81], v[148:151], v[208:211], v[78:81]
	v_mfma_f32_16x16x32_bf16 v[74:77], v[162:165], v[208:211], v[74:77]
	v_mfma_f32_16x16x32_bf16 v[126:129], v[158:161], v[188:191], v[126:129]
	v_mfma_f32_16x16x32_bf16 v[122:125], v[180:183], v[188:191], v[122:125]
	v_mfma_f32_16x16x32_bf16 v[110:113], v[158:161], v[196:199], v[110:113]
	v_mfma_f32_16x16x32_bf16 v[106:109], v[180:183], v[196:199], v[106:109]
	v_mfma_f32_16x16x32_bf16 v[94:97], v[158:161], v[204:207], v[94:97]
	v_mfma_f32_16x16x32_bf16 v[90:93], v[180:183], v[204:207], v[90:93]
	v_mfma_f32_16x16x32_bf16 v[78:81], v[158:161], v[212:215], v[78:81]
	v_mfma_f32_16x16x32_bf16 v[74:77], v[180:183], v[212:215], v[74:77]
	s_setprio 0
	s_barrier
	s_add_i32 s60, 0, 0x14000
	v_add_u32_e32 v134, s60, v155
	s_add_i32 s58, s58, s6
	ds_read_b128 v[216:219], v134
	ds_read_b128 v[220:223], v134 offset:1024
	ds_read_b128 v[224:227], v134 offset:2048
	ds_read_b128 v[228:231], v134 offset:3072
	v_lshl_add_u64 v[134:135], s[26:27], 0, v[0:1]
	s_mov_b32 m0, s58
	v_lshl_add_u64 v[152:153], s[26:27], 0, v[138:139]
	global_load_lds_dwordx4 v[134:135], off
	s_add_i32 m0, s58, 0x2000
	s_nop 0
	global_load_lds_dwordx4 v[152:153], off
	s_barrier
	s_waitcnt lgkmcnt(0)
	s_setprio 1
	s_waitcnt lgkmcnt(0)
	v_mfma_f32_16x16x32_bf16 v[118:121], v[216:219], v[184:187], v[118:121]
	v_mfma_f32_16x16x32_bf16 v[114:117], v[224:227], v[184:187], v[114:117]
	v_mfma_f32_16x16x32_bf16 v[102:105], v[216:219], v[192:195], v[102:105]
	v_mfma_f32_16x16x32_bf16 v[98:101], v[224:227], v[192:195], v[98:101]
	v_mfma_f32_16x16x32_bf16 v[86:89], v[216:219], v[200:203], v[86:89]
	v_mfma_f32_16x16x32_bf16 v[82:85], v[224:227], v[200:203], v[82:85]
	v_mfma_f32_16x16x32_bf16 v[70:73], v[216:219], v[208:211], v[70:73]
	v_mfma_f32_16x16x32_bf16 v[66:69], v[224:227], v[208:211], v[66:69]
	v_mfma_f32_16x16x32_bf16 v[118:121], v[220:223], v[188:191], v[118:121]
	v_mfma_f32_16x16x32_bf16 v[114:117], v[228:231], v[188:191], v[114:117]
	v_mfma_f32_16x16x32_bf16 v[102:105], v[220:223], v[196:199], v[102:105]
	v_mfma_f32_16x16x32_bf16 v[98:101], v[228:231], v[196:199], v[98:101]
	v_mfma_f32_16x16x32_bf16 v[86:89], v[220:223], v[204:207], v[86:89]
	v_mfma_f32_16x16x32_bf16 v[82:85], v[228:231], v[204:207], v[82:85]
	v_mfma_f32_16x16x32_bf16 v[70:73], v[220:223], v[212:215], v[70:73]
	v_mfma_f32_16x16x32_bf16 v[66:69], v[228:231], v[212:215], v[66:69]
	s_setprio 0
	s_mov_b32 m0, s7
	v_lshl_add_u64 v[166:167], s[44:45], 0, v[142:143]
	s_barrier
	ds_read_b128 v[184:187], v157 offset:16384
	ds_read_b128 v[188:191], v157 offset:17408
	ds_read_b128 v[192:195], v157 offset:18432
	ds_read_b128 v[196:199], v157 offset:19456
	ds_read_b128 v[200:203], v157 offset:20480
	ds_read_b128 v[204:207], v157 offset:21504
	ds_read_b128 v[208:211], v157 offset:22528
	ds_read_b128 v[212:215], v157 offset:23552
	global_load_lds_dwordx4 v[166:167], off
	v_lshl_add_u64 v[232:233], s[44:45], 0, v[140:141]
	s_mov_b32 m0, s14
	s_nop 0
	global_load_lds_dwordx4 v[232:233], off
	s_barrier
	s_waitcnt lgkmcnt(0)
	s_setprio 1
	s_waitcnt lgkmcnt(0)
	v_mfma_f32_16x16x32_bf16 v[62:65], v[148:151], v[184:187], v[62:65]
	v_mfma_f32_16x16x32_bf16 v[58:61], v[162:165], v[184:187], v[58:61]
	v_mfma_f32_16x16x32_bf16 v[46:49], v[148:151], v[192:195], v[46:49]
	v_mfma_f32_16x16x32_bf16 v[42:45], v[162:165], v[192:195], v[42:45]
	v_mfma_f32_16x16x32_bf16 v[30:33], v[148:151], v[200:203], v[30:33]
	v_mfma_f32_16x16x32_bf16 v[26:29], v[162:165], v[200:203], v[26:29]
	v_mfma_f32_16x16x32_bf16 v[14:17], v[148:151], v[208:211], v[14:17]
	v_mfma_f32_16x16x32_bf16 v[10:13], v[162:165], v[208:211], v[10:13]
	v_mfma_f32_16x16x32_bf16 v[62:65], v[158:161], v[188:191], v[62:65]
	v_mfma_f32_16x16x32_bf16 v[58:61], v[180:183], v[188:191], v[58:61]
	v_mfma_f32_16x16x32_bf16 v[46:49], v[158:161], v[196:199], v[46:49]
	v_mfma_f32_16x16x32_bf16 v[42:45], v[180:183], v[196:199], v[42:45]
	v_mfma_f32_16x16x32_bf16 v[30:33], v[158:161], v[204:207], v[30:33]
	v_mfma_f32_16x16x32_bf16 v[26:29], v[180:183], v[204:207], v[26:29]
	v_mfma_f32_16x16x32_bf16 v[14:17], v[158:161], v[212:215], v[14:17]
	v_mfma_f32_16x16x32_bf16 v[10:13], v[180:183], v[212:215], v[10:13]
	s_setprio 0
	s_barrier
	s_add_u32 s58, s26, 0x80000
	s_addc_u32 s59, s27, 0
	s_add_i32 s60, s60, s6
	s_mov_b32 m0, s60
	s_nop 0
	global_load_lds_dwordx4 v0, s[58:59]
	s_add_i32 m0, s60, 0x2000
	s_nop 0
	global_load_lds_dwordx4 v138, s[58:59]
	s_waitcnt vmcnt(6)
	s_barrier
	s_setprio 1
	v_mfma_f32_16x16x32_bf16 v[54:57], v[216:219], v[184:187], v[54:57]
	v_mfma_f32_16x16x32_bf16 v[50:53], v[224:227], v[184:187], v[50:53]
	v_mfma_f32_16x16x32_bf16 v[38:41], v[216:219], v[192:195], v[38:41]
	v_mfma_f32_16x16x32_bf16 v[34:37], v[224:227], v[192:195], v[34:37]
	v_mfma_f32_16x16x32_bf16 v[22:25], v[216:219], v[200:203], v[22:25]
	v_mfma_f32_16x16x32_bf16 v[18:21], v[224:227], v[200:203], v[18:21]
	v_mfma_f32_16x16x32_bf16 v[6:9], v[216:219], v[208:211], v[6:9]
	v_mfma_f32_16x16x32_bf16 v[2:5], v[224:227], v[208:211], v[2:5]
	v_mfma_f32_16x16x32_bf16 v[54:57], v[220:223], v[188:191], v[54:57]
	v_mfma_f32_16x16x32_bf16 v[50:53], v[228:231], v[188:191], v[50:53]
	v_mfma_f32_16x16x32_bf16 v[38:41], v[220:223], v[196:199], v[38:41]
	v_mfma_f32_16x16x32_bf16 v[34:37], v[228:231], v[196:199], v[34:37]
	v_mfma_f32_16x16x32_bf16 v[22:25], v[220:223], v[204:207], v[22:25]
	v_mfma_f32_16x16x32_bf16 v[18:21], v[228:231], v[204:207], v[18:21]
	v_mfma_f32_16x16x32_bf16 v[6:9], v[220:223], v[212:215], v[6:9]
	v_mfma_f32_16x16x32_bf16 v[2:5], v[228:231], v[212:215], v[2:5]
	s_setprio 0
	s_add_i32 s58, 0, 0x18000
	v_add_u32_e32 v180, s58, v155
	s_barrier
	ds_read_b128 v[148:151], v180
	ds_read_b128 v[158:161], v180 offset:1024
	ds_read_b128 v[162:165], v180 offset:2048
	ds_read_b128 v[180:183], v180 offset:3072
	s_add_u32 s44, s44, 0x80000
	s_addc_u32 s45, s45, 0
	s_mov_b32 m0, s46
	ds_read_b128 v[184:187], v157 offset:32768
	ds_read_b128 v[188:191], v157 offset:33792
	ds_read_b128 v[192:195], v157 offset:34816
	ds_read_b128 v[196:199], v157 offset:35840
	ds_read_b128 v[200:203], v157 offset:36864
	ds_read_b128 v[204:207], v157 offset:37888
	ds_read_b128 v[208:211], v157 offset:38912
	ds_read_b128 v[212:215], v157 offset:39936
	global_load_lds_dwordx4 v142, s[44:45]
	s_mov_b32 m0, s47
	s_nop 0
	global_load_lds_dwordx4 v140, s[44:45]
	s_waitcnt lgkmcnt(8)
	s_barrier
	s_waitcnt lgkmcnt(0)
	s_setprio 1
	s_waitcnt lgkmcnt(0)
	v_mfma_f32_16x16x32_bf16 v[126:129], v[148:151], v[184:187], v[126:129]
	v_mfma_f32_16x16x32_bf16 v[122:125], v[162:165], v[184:187], v[122:125]
	v_mfma_f32_16x16x32_bf16 v[110:113], v[148:151], v[192:195], v[110:113]
	v_mfma_f32_16x16x32_bf16 v[106:109], v[162:165], v[192:195], v[106:109]
	v_mfma_f32_16x16x32_bf16 v[94:97], v[148:151], v[200:203], v[94:97]
	v_mfma_f32_16x16x32_bf16 v[90:93], v[162:165], v[200:203], v[90:93]
	v_mfma_f32_16x16x32_bf16 v[78:81], v[148:151], v[208:211], v[78:81]
	v_mfma_f32_16x16x32_bf16 v[74:77], v[162:165], v[208:211], v[74:77]
	v_mfma_f32_16x16x32_bf16 v[126:129], v[158:161], v[188:191], v[126:129]
	v_mfma_f32_16x16x32_bf16 v[122:125], v[180:183], v[188:191], v[122:125]
	v_mfma_f32_16x16x32_bf16 v[110:113], v[158:161], v[196:199], v[110:113]
	v_mfma_f32_16x16x32_bf16 v[106:109], v[180:183], v[196:199], v[106:109]
	v_mfma_f32_16x16x32_bf16 v[94:97], v[158:161], v[204:207], v[94:97]
	v_mfma_f32_16x16x32_bf16 v[90:93], v[180:183], v[204:207], v[90:93]
	v_mfma_f32_16x16x32_bf16 v[78:81], v[158:161], v[212:215], v[78:81]
	v_mfma_f32_16x16x32_bf16 v[74:77], v[180:183], v[212:215], v[74:77]
	s_setprio 0
	s_barrier
	s_add_i32 s44, 0, 0x1c000
	s_add_i32 s45, s58, s6
	v_add_u32_e32 v228, s44, v155
	v_lshl_add_u64 v[134:135], v[134:135], 0, s[10:11]
	s_mov_b32 m0, s45
	ds_read_b128 v[216:219], v228
	ds_read_b128 v[220:223], v228 offset:1024
	ds_read_b128 v[224:227], v228 offset:2048
	ds_read_b128 v[228:231], v228 offset:3072
	global_load_lds_dwordx4 v[134:135], off
	v_lshl_add_u64 v[134:135], v[152:153], 0, s[10:11]
	s_add_i32 m0, s45, 0x2000
	s_nop 0
	global_load_lds_dwordx4 v[134:135], off
	s_barrier
	s_waitcnt lgkmcnt(0)
	s_setprio 1
	s_waitcnt lgkmcnt(0)
	v_mfma_f32_16x16x32_bf16 v[118:121], v[216:219], v[184:187], v[118:121]
	v_mfma_f32_16x16x32_bf16 v[114:117], v[224:227], v[184:187], v[114:117]
	v_mfma_f32_16x16x32_bf16 v[102:105], v[216:219], v[192:195], v[102:105]
	v_mfma_f32_16x16x32_bf16 v[98:101], v[224:227], v[192:195], v[98:101]
	v_mfma_f32_16x16x32_bf16 v[86:89], v[216:219], v[200:203], v[86:89]
	v_mfma_f32_16x16x32_bf16 v[82:85], v[224:227], v[200:203], v[82:85]
	v_mfma_f32_16x16x32_bf16 v[70:73], v[216:219], v[208:211], v[70:73]
	v_mfma_f32_16x16x32_bf16 v[66:69], v[224:227], v[208:211], v[66:69]
	v_mfma_f32_16x16x32_bf16 v[118:121], v[220:223], v[188:191], v[118:121]
	v_mfma_f32_16x16x32_bf16 v[114:117], v[228:231], v[188:191], v[114:117]
	v_mfma_f32_16x16x32_bf16 v[102:105], v[220:223], v[196:199], v[102:105]
	v_mfma_f32_16x16x32_bf16 v[98:101], v[228:231], v[196:199], v[98:101]
	v_mfma_f32_16x16x32_bf16 v[86:89], v[220:223], v[204:207], v[86:89]
	v_mfma_f32_16x16x32_bf16 v[82:85], v[228:231], v[204:207], v[82:85]
	v_mfma_f32_16x16x32_bf16 v[70:73], v[220:223], v[212:215], v[70:73]
	v_mfma_f32_16x16x32_bf16 v[66:69], v[228:231], v[212:215], v[66:69]
	s_setprio 0
	s_mov_b32 m0, s48
	v_lshl_add_u64 v[134:135], v[166:167], 0, s[10:11]
	s_barrier
	ds_read_b128 v[184:187], v157 offset:49152
	ds_read_b128 v[188:191], v157 offset:50176
	ds_read_b128 v[192:195], v157 offset:51200
	ds_read_b128 v[196:199], v157 offset:52224
	ds_read_b128 v[200:203], v157 offset:53248
	ds_read_b128 v[204:207], v157 offset:54272
	ds_read_b128 v[208:211], v157 offset:55296
	ds_read_b128 v[212:215], v157 offset:56320
	global_load_lds_dwordx4 v[134:135], off
	v_lshl_add_u64 v[134:135], v[232:233], 0, s[10:11]
	s_mov_b32 m0, s49
	s_nop 0
	global_load_lds_dwordx4 v[134:135], off
	s_barrier
	s_waitcnt lgkmcnt(0)
	s_setprio 1
	s_waitcnt lgkmcnt(0)
	v_mfma_f32_16x16x32_bf16 v[62:65], v[148:151], v[184:187], v[62:65]
	v_mfma_f32_16x16x32_bf16 v[58:61], v[162:165], v[184:187], v[58:61]
	v_mfma_f32_16x16x32_bf16 v[46:49], v[148:151], v[192:195], v[46:49]
	v_mfma_f32_16x16x32_bf16 v[42:45], v[162:165], v[192:195], v[42:45]
	v_mfma_f32_16x16x32_bf16 v[30:33], v[148:151], v[200:203], v[30:33]
	v_mfma_f32_16x16x32_bf16 v[26:29], v[162:165], v[200:203], v[26:29]
	v_mfma_f32_16x16x32_bf16 v[14:17], v[148:151], v[208:211], v[14:17]
	v_mfma_f32_16x16x32_bf16 v[10:13], v[162:165], v[208:211], v[10:13]
	v_mfma_f32_16x16x32_bf16 v[62:65], v[158:161], v[188:191], v[62:65]
	v_mfma_f32_16x16x32_bf16 v[58:61], v[180:183], v[188:191], v[58:61]
	v_mfma_f32_16x16x32_bf16 v[46:49], v[158:161], v[196:199], v[46:49]
	v_mfma_f32_16x16x32_bf16 v[42:45], v[180:183], v[196:199], v[42:45]
	v_mfma_f32_16x16x32_bf16 v[30:33], v[158:161], v[204:207], v[30:33]
	v_mfma_f32_16x16x32_bf16 v[26:29], v[180:183], v[204:207], v[26:29]
	v_mfma_f32_16x16x32_bf16 v[14:17], v[158:161], v[212:215], v[14:17]
	v_mfma_f32_16x16x32_bf16 v[10:13], v[180:183], v[212:215], v[10:13]
	s_setprio 0
	s_barrier
	s_add_u32 s26, s26, 0x80080
	s_addc_u32 s27, s27, 0
	s_add_i32 s44, s44, s6
	s_mov_b32 m0, s44
	s_nop 0
	global_load_lds_dwordx4 v0, s[26:27]
	s_add_i32 m0, s44, 0x2000
	s_nop 0
	global_load_lds_dwordx4 v138, s[26:27]
	s_waitcnt vmcnt(6)
	s_barrier
	s_setprio 1
	v_mfma_f32_16x16x32_bf16 v[54:57], v[216:219], v[184:187], v[54:57]
	v_mfma_f32_16x16x32_bf16 v[50:53], v[224:227], v[184:187], v[50:53]
	v_mfma_f32_16x16x32_bf16 v[38:41], v[216:219], v[192:195], v[38:41]
	v_mfma_f32_16x16x32_bf16 v[34:37], v[224:227], v[192:195], v[34:37]
	v_mfma_f32_16x16x32_bf16 v[22:25], v[216:219], v[200:203], v[22:25]
	v_mfma_f32_16x16x32_bf16 v[18:21], v[224:227], v[200:203], v[18:21]
	v_mfma_f32_16x16x32_bf16 v[6:9], v[216:219], v[208:211], v[6:9]
	v_mfma_f32_16x16x32_bf16 v[2:5], v[224:227], v[208:211], v[2:5]
	v_mfma_f32_16x16x32_bf16 v[54:57], v[220:223], v[188:191], v[54:57]
	v_mfma_f32_16x16x32_bf16 v[50:53], v[228:231], v[188:191], v[50:53]
	v_mfma_f32_16x16x32_bf16 v[38:41], v[220:223], v[196:199], v[38:41]
	v_mfma_f32_16x16x32_bf16 v[34:37], v[228:231], v[196:199], v[34:37]
	v_mfma_f32_16x16x32_bf16 v[22:25], v[220:223], v[204:207], v[22:25]
	v_mfma_f32_16x16x32_bf16 v[18:21], v[228:231], v[204:207], v[18:21]
	v_mfma_f32_16x16x32_bf16 v[6:9], v[220:223], v[212:215], v[6:9]
	v_mfma_f32_16x16x32_bf16 v[2:5], v[228:231], v[212:215], v[2:5]
	s_setprio 0
	s_add_i32 s57, s57, 2
	s_add_u32 s42, s42, 0x100
	s_addc_u32 s43, s43, 0
	s_add_u32 s55, s55, 0x100
	s_addc_u32 s56, s56, 0
	s_cmp_gt_u32 s57, 29
	s_barrier
	s_cbranch_scc0 .LBB0_1034
	v_lshl_add_u32 v150, s52, 8, v154
	v_lshl_or_b32 v134, s51, 8, v156
	v_ashrrev_i32_e32 v151, 31, v150
	v_ashrrev_i32_e32 v135, 31, v134
	v_lshlrev_b64 v[148:149], 13, v[150:151]
	v_lshl_add_u64 v[148:149], s[76:77], 0, v[148:149]
	v_lshlrev_b64 v[152:153], 2, v[134:135]
	v_lshl_add_u64 v[158:159], v[148:149], 0, v[152:153]
	v_readlane_b32 s56, v254, 30
	v_readlane_b32 s54, v254, 32
	v_readlane_b32 s60, v254, 39
	s_mov_b32 s51, s0
	s_mov_b32 s52, s22
	s_mov_b64 s[42:43], s[24:25]
	v_readlane_b32 s57, v254, 31
	v_readlane_b32 s55, v254, 33
	v_readlane_b32 s44, v254, 46
	v_readlane_b32 s61, v254, 40
	v_readlane_b32 s45, v254, 47
	v_mov_b64_e32 v[162:163], v[158:159]
	global_load_dwordx4 v[180:183], v[162:163], off
	global_load_dwordx4 v[184:187], v[162:163], off offset:16
	global_load_dwordx4 v[188:191], v[162:163], off offset:512
	global_load_dwordx4 v[192:195], v[162:163], off offset:528
	s_mov_b64 s[26:27], 0x20000
	v_lshl_add_u64 v[164:165], v[158:159], 0, s[26:27]
	global_load_dwordx4 v[196:199], v[164:165], off
	global_load_dwordx4 v[200:203], v[164:165], off offset:16
	global_load_dwordx4 v[204:207], v[164:165], off offset:512
	global_load_dwordx4 v[208:211], v[164:165], off offset:528
	s_mov_b64 s[26:27], 0x40000
	v_lshl_add_u64 v[150:151], v[158:159], 0, s[26:27]
	global_load_dwordx4 v[212:215], v[150:151], off
	global_load_dwordx4 v[216:219], v[150:151], off offset:16
	global_load_dwordx4 v[220:223], v[150:151], off offset:512
	global_load_dwordx4 v[224:227], v[150:151], off offset:528
	s_waitcnt vmcnt(8)
	v_pk_add_f32 v[126:127], v[126:127], v[180:181]
	v_pk_add_f32 v[128:129], v[128:129], v[182:183]
	v_pk_add_f32 v[122:123], v[122:123], v[184:185]
	v_pk_add_f32 v[124:125], v[124:125], v[186:187]
	v_pk_add_f32 v[118:119], v[118:119], v[188:189]
	v_pk_add_f32 v[120:121], v[120:121], v[190:191]
	v_pk_add_f32 v[114:115], v[114:115], v[192:193]
	v_pk_add_f32 v[116:117], v[116:117], v[194:195]
	global_store_dwordx4 v[162:163], v[126:129], off
	global_store_dwordx4 v[162:163], v[122:125], off offset:16
	global_store_dwordx4 v[162:163], v[118:121], off offset:512
	global_store_dwordx4 v[162:163], v[114:117], off offset:528
	s_mov_b64 s[26:27], 0x60000
	v_lshl_add_u64 v[228:229], v[158:159], 0, s[26:27]
	global_load_dwordx4 v[180:183], v[228:229], off
	global_load_dwordx4 v[184:187], v[228:229], off offset:16
	global_load_dwordx4 v[188:191], v[228:229], off offset:512
	global_load_dwordx4 v[192:195], v[228:229], off offset:528
	s_waitcnt vmcnt(12)
	v_pk_add_f32 v[110:111], v[110:111], v[196:197]
	v_pk_add_f32 v[112:113], v[112:113], v[198:199]
	v_pk_add_f32 v[106:107], v[106:107], v[200:201]
	v_pk_add_f32 v[108:109], v[108:109], v[202:203]
	v_pk_add_f32 v[102:103], v[102:103], v[204:205]
	v_pk_add_f32 v[104:105], v[104:105], v[206:207]
	v_pk_add_f32 v[98:99], v[98:99], v[208:209]
	v_pk_add_f32 v[100:101], v[100:101], v[210:211]
	global_store_dwordx4 v[164:165], v[110:113], off
	global_store_dwordx4 v[164:165], v[106:109], off offset:16
	global_store_dwordx4 v[164:165], v[102:105], off offset:512
	global_store_dwordx4 v[164:165], v[98:101], off offset:528
	s_mov_b64 s[26:27], 0x100000
	v_lshl_add_u64 v[162:163], v[158:159], 0, s[26:27]
	global_load_dwordx4 v[196:199], v[162:163], off
	global_load_dwordx4 v[200:203], v[162:163], off offset:16
	global_load_dwordx4 v[204:207], v[162:163], off offset:512
	global_load_dwordx4 v[208:211], v[162:163], off offset:528
	s_waitcnt vmcnt(16)
	v_pk_add_f32 v[94:95], v[94:95], v[212:213]
	v_pk_add_f32 v[96:97], v[96:97], v[214:215]
	v_pk_add_f32 v[90:91], v[90:91], v[216:217]
	v_pk_add_f32 v[92:93], v[92:93], v[218:219]
	v_pk_add_f32 v[86:87], v[86:87], v[220:221]
	v_pk_add_f32 v[88:89], v[88:89], v[222:223]
	v_pk_add_f32 v[82:83], v[82:83], v[224:225]
	v_pk_add_f32 v[84:85], v[84:85], v[226:227]
	global_store_dwordx4 v[150:151], v[94:97], off
	global_store_dwordx4 v[150:151], v[90:93], off offset:16
	global_store_dwordx4 v[150:151], v[86:89], off offset:512
	global_store_dwordx4 v[150:151], v[82:85], off offset:528
	s_mov_b64 s[26:27], 0x120000
	v_lshl_add_u64 v[164:165], v[158:159], 0, s[26:27]
	global_load_dwordx4 v[212:215], v[164:165], off
	global_load_dwordx4 v[216:219], v[164:165], off offset:16
	global_load_dwordx4 v[220:223], v[164:165], off offset:512
	global_load_dwordx4 v[224:227], v[164:165], off offset:528
	s_waitcnt vmcnt(16)
	v_pk_add_f32 v[78:79], v[78:79], v[180:181]
	v_pk_add_f32 v[80:81], v[80:81], v[182:183]
	v_pk_add_f32 v[74:75], v[74:75], v[184:185]
	v_pk_add_f32 v[76:77], v[76:77], v[186:187]
	v_pk_add_f32 v[70:71], v[70:71], v[188:189]
	v_pk_add_f32 v[72:73], v[72:73], v[190:191]
	v_pk_add_f32 v[66:67], v[66:67], v[192:193]
	v_pk_add_f32 v[68:69], v[68:69], v[194:195]
	global_store_dwordx4 v[228:229], v[78:81], off
	global_store_dwordx4 v[228:229], v[74:77], off offset:16
	global_store_dwordx4 v[228:229], v[70:73], off offset:512
	global_store_dwordx4 v[228:229], v[66:69], off offset:528
	s_mov_b64 s[26:27], 0x140000
	v_lshl_add_u64 v[150:151], v[158:159], 0, s[26:27]
	global_load_dwordx4 v[180:183], v[150:151], off
	global_load_dwordx4 v[184:187], v[150:151], off offset:16
	global_load_dwordx4 v[188:191], v[150:151], off offset:512
	global_load_dwordx4 v[192:195], v[150:151], off offset:528
	s_waitcnt vmcnt(16)
	v_pk_add_f32 v[62:63], v[62:63], v[196:197]
	v_pk_add_f32 v[64:65], v[64:65], v[198:199]
	v_pk_add_f32 v[58:59], v[58:59], v[200:201]
	v_pk_add_f32 v[60:61], v[60:61], v[202:203]
	v_pk_add_f32 v[54:55], v[54:55], v[204:205]
	v_pk_add_f32 v[56:57], v[56:57], v[206:207]
	v_pk_add_f32 v[50:51], v[50:51], v[208:209]
	v_pk_add_f32 v[52:53], v[52:53], v[210:211]
	global_store_dwordx4 v[162:163], v[62:65], off
	global_store_dwordx4 v[162:163], v[58:61], off offset:16
	global_store_dwordx4 v[162:163], v[54:57], off offset:512
	global_store_dwordx4 v[162:163], v[50:53], off offset:528
	s_mov_b64 s[26:27], 0x160000
	v_lshl_add_u64 v[228:229], v[158:159], 0, s[26:27]
	global_load_dwordx4 v[196:199], v[228:229], off
	global_load_dwordx4 v[200:203], v[228:229], off offset:16
	global_load_dwordx4 v[204:207], v[228:229], off offset:512
	global_load_dwordx4 v[208:211], v[228:229], off offset:528
	s_waitcnt vmcnt(16)
	v_pk_add_f32 v[46:47], v[46:47], v[212:213]
	v_pk_add_f32 v[48:49], v[48:49], v[214:215]
	v_pk_add_f32 v[42:43], v[42:43], v[216:217]
	v_pk_add_f32 v[44:45], v[44:45], v[218:219]
	v_pk_add_f32 v[38:39], v[38:39], v[220:221]
	v_pk_add_f32 v[40:41], v[40:41], v[222:223]
	v_pk_add_f32 v[34:35], v[34:35], v[224:225]
	v_pk_add_f32 v[36:37], v[36:37], v[226:227]
	global_store_dwordx4 v[164:165], v[46:49], off
	global_store_dwordx4 v[164:165], v[42:45], off offset:16
	global_store_dwordx4 v[164:165], v[38:41], off offset:512
	global_store_dwordx4 v[164:165], v[34:37], off offset:528
	s_waitcnt vmcnt(12)
	v_pk_add_f32 v[30:31], v[30:31], v[180:181]
	v_pk_add_f32 v[32:33], v[32:33], v[182:183]
	v_pk_add_f32 v[26:27], v[26:27], v[184:185]
	v_pk_add_f32 v[28:29], v[28:29], v[186:187]
	v_pk_add_f32 v[22:23], v[22:23], v[188:189]
	v_pk_add_f32 v[24:25], v[24:25], v[190:191]
	v_pk_add_f32 v[18:19], v[18:19], v[192:193]
	v_pk_add_f32 v[20:21], v[20:21], v[194:195]
	global_store_dwordx4 v[150:151], v[30:33], off
	global_store_dwordx4 v[150:151], v[26:29], off offset:16
	global_store_dwordx4 v[150:151], v[22:25], off offset:512
	global_store_dwordx4 v[150:151], v[18:21], off offset:528
	s_waitcnt vmcnt(8)
	v_pk_add_f32 v[14:15], v[14:15], v[196:197]
	v_pk_add_f32 v[16:17], v[16:17], v[198:199]
	v_pk_add_f32 v[10:11], v[10:11], v[200:201]
	v_pk_add_f32 v[12:13], v[12:13], v[202:203]
	v_pk_add_f32 v[6:7], v[6:7], v[204:205]
	v_pk_add_f32 v[8:9], v[8:9], v[206:207]
	v_pk_add_f32 v[2:3], v[2:3], v[208:209]
	v_pk_add_f32 v[4:5], v[4:5], v[210:211]
	global_store_dwordx4 v[228:229], v[14:17], off
	global_store_dwordx4 v[228:229], v[10:13], off offset:16
	global_store_dwordx4 v[228:229], v[6:9], off offset:512
	global_store_dwordx4 v[228:229], v[2:5], off offset:528
	s_mov_b32 s1, 0x160000
	s_and_b64 vcc, exec, s[38:39]
	s_mov_b64 s[26:27], s[40:41]
	s_cbranch_vccz .LBB0_1027
	s_waitcnt vmcnt(0)
	v_readlane_b32 s52, v254, 26
	v_readlane_b32 s50, v254, 28
	s_mov_b64 s[58:59], s[84:85]
	s_cmpk_gt_u32 s4, 0xff
	v_readlane_b32 s53, v254, 27
	v_readlane_b32 s51, v254, 29
	s_cbranch_scc1 .LBB0_1038
	s_barrier
